# speedup vs baseline: 1.0320x; 1.0168x over previous
.LBB0_78:
	s_sext_i32_i16 s6, s6
	v_ashrrev_i32_e32 v0, 1, v211
	v_and_b32_e32 v0, 0xffffffc0, v0
	s_lshl_b32 s6, s6, 7
	v_add_u32_e32 v0, s8, v0
	s_waitcnt vmcnt(7)
	v_and_or_b32 v130, v211, 64, s6
	s_waitcnt vmcnt(6)
	v_and_or_b32 v134, v211, 31, v0
	v_ashrrev_i32_e32 v131, 31, v130
	v_lshrrev_b32_e32 v0, 1, v211
	v_lshl_add_u64 v[130:131], v[130:131], 1, s[0:1]
	v_and_b32_e32 v0, 16, v0
	v_lshl_add_u64 v[130:131], v[130:131], 0, v[0:1]
	v_mul_f32_e32 v0, 0xbfb8aa3b, v114
	v_exp_f32_e32 v136, v0
	v_mul_f32_e32 v0, 0xbfb8aa3b, v115
	v_exp_f32_e32 v137, v0
	s_movk_i32 s8, 0x1600
	v_mad_i64_i32 v[132:133], s[6:7], v134, s8, v[130:131]
	v_pk_add_f32 v[136:137], v[136:137], 1.0 op_sel_hi:[1,0]
	s_nop 2
	s_waitcnt vmcnt(5)
	s_nop 4
	v_rcp_f32_e32 v0, v137
	s_nop 0
	v_mul_f32_e32 v115, v115, v0
	s_nop 4
	v_rcp_f32_e32 v0, v136
	s_nop 0
	v_mul_f32_e32 v114, v114, v0
	v_mul_f32_e32 v0, 0xbfb8aa3b, v116
	v_pk_mul_f32 v[98:99], v[98:99], v[114:115]
	v_exp_f32_e32 v114, v0
	v_mul_f32_e32 v0, 0xbfb8aa3b, v117
	v_exp_f32_e32 v115, v0
	v_cvt_pk_bf16_f32 v98, v98, v99
	v_pk_add_f32 v[114:115], v[114:115], 1.0 op_sel_hi:[1,0]
	s_nop 4
	v_rcp_f32_e32 v0, v115
	s_nop 0
	v_mul_f32_e32 v115, v117, v0
	s_nop 4
	v_rcp_f32_e32 v0, v114
	s_nop 0
	v_mul_f32_e32 v114, v116, v0
	v_pk_mul_f32 v[100:101], v[100:101], v[114:115]
	v_mul_f32_e32 v0, 0xbfb8aa3b, v118
	v_cvt_pk_bf16_f32 v99, v100, v101
	v_exp_f32_e32 v100, v0
	v_mul_f32_e32 v0, 0xbfb8aa3b, v119
	v_exp_f32_e32 v101, v0
	s_nop 0
	v_pk_add_f32 v[100:101], v[100:101], 1.0 op_sel_hi:[1,0]
	s_nop 4
	v_rcp_f32_e32 v0, v101
	s_nop 0
	v_mul_f32_e32 v101, v119, v0
	s_nop 4
	v_rcp_f32_e32 v0, v100
	s_nop 0
	v_mul_f32_e32 v100, v118, v0
	v_mul_f32_e32 v0, 0xbfb8aa3b, v120
	v_pk_mul_f32 v[100:101], v[102:103], v[100:101]
	v_exp_f32_e32 v102, v0
	v_mul_f32_e32 v0, 0xbfb8aa3b, v121
	v_exp_f32_e32 v103, v0
	v_cvt_pk_bf16_f32 v100, v100, v101
	s_nop 1
	v_permlane32_swap_b32_e32 v98, v100
	v_pk_add_f32 v[102:103], v[102:103], 1.0 op_sel_hi:[1,0]
	s_nop 4
	v_rcp_f32_e32 v0, v103
	s_nop 0
	v_mul_f32_e32 v103, v121, v0
	s_nop 4
	v_rcp_f32_e32 v0, v102
	s_nop 0
	v_mul_f32_e32 v102, v120, v0
	v_pk_mul_f32 v[102:103], v[104:105], v[102:103]
	v_mul_f32_e32 v0, 0xbfb8aa3b, v122
	v_cvt_pk_bf16_f32 v101, v102, v103
	s_nop 1
	v_permlane32_swap_b32_e32 v99, v101
	global_store_dwordx4 v[132:133], v[98:101], off
	s_nop 1
	v_exp_f32_e32 v98, v0
	v_mul_f32_e32 v0, 0xbfb8aa3b, v123
	v_exp_f32_e32 v99, v0
	s_nop 0
	v_pk_add_f32 v[98:99], v[98:99], 1.0 op_sel_hi:[1,0]
	s_nop 4
	v_rcp_f32_e32 v0, v99
	s_nop 0
	v_mul_f32_e32 v99, v123, v0
	s_nop 4
	v_rcp_f32_e32 v0, v98
	s_nop 0
	v_mul_f32_e32 v98, v122, v0
	v_mul_f32_e32 v0, 0xbfb8aa3b, v124
	v_exp_f32_e32 v100, v0
	v_mul_f32_e32 v0, 0xbfb8aa3b, v125
	v_exp_f32_e32 v101, v0
	v_pk_mul_f32 v[98:99], v[106:107], v[98:99]
	v_pk_add_f32 v[100:101], v[100:101], 1.0 op_sel_hi:[1,0]
	s_nop 2
	v_cvt_pk_bf16_f32 v98, v98, v99
	s_nop 4
	v_rcp_f32_e32 v0, v101
	s_nop 0
	v_mul_f32_e32 v101, v125, v0
	s_nop 4
	v_rcp_f32_e32 v0, v100
	s_nop 0
	v_mul_f32_e32 v100, v124, v0
	v_pk_mul_f32 v[100:101], v[108:109], v[100:101]
	v_mul_f32_e32 v0, 0xbfb8aa3b, v126
	v_cvt_pk_bf16_f32 v99, v100, v101
	v_exp_f32_e32 v100, v0
	v_mul_f32_e32 v0, 0xbfb8aa3b, v127
	v_exp_f32_e32 v101, v0
	s_nop 0
	v_pk_add_f32 v[100:101], v[100:101], 1.0 op_sel_hi:[1,0]
	s_nop 4
	v_rcp_f32_e32 v0, v101
	s_nop 0
	v_mul_f32_e32 v101, v127, v0
	s_nop 4
	v_rcp_f32_e32 v0, v100
	s_nop 0
	v_mul_f32_e32 v100, v126, v0
	v_mul_f32_e32 v0, 0xbfb8aa3b, v128
	v_exp_f32_e32 v102, v0
	v_mul_f32_e32 v0, 0xbfb8aa3b, v129
	v_exp_f32_e32 v103, v0
	v_pk_mul_f32 v[100:101], v[110:111], v[100:101]
	v_pk_add_f32 v[102:103], v[102:103], 1.0 op_sel_hi:[1,0]
	s_nop 2
	v_cvt_pk_bf16_f32 v100, v100, v101
	s_nop 1
	v_permlane32_swap_b32_e32 v98, v100
	s_nop 4
	v_rcp_f32_e32 v0, v103
	s_nop 0
	v_mul_f32_e32 v103, v129, v0
	s_nop 4
	v_rcp_f32_e32 v0, v102
	s_nop 0
	v_mul_f32_e32 v102, v128, v0
	v_pk_mul_f32 v[102:103], v[112:113], v[102:103]
	v_mul_f32_e32 v0, 0xbfb8aa3b, v82
	v_cvt_pk_bf16_f32 v101, v102, v103
	s_nop 1
	v_permlane32_swap_b32_e32 v99, v101
	global_store_dwordx4 v[132:133], v[98:101], off offset:32
	s_nop 1
	v_exp_f32_e32 v98, v0
	v_mul_f32_e32 v0, 0xbfb8aa3b, v83
	v_exp_f32_e32 v99, v0
	s_nop 0
	v_pk_add_f32 v[98:99], v[98:99], 1.0 op_sel_hi:[1,0]
	s_nop 4
	v_rcp_f32_e32 v0, v99
	s_nop 0
	v_mul_f32_e32 v83, v83, v0
	s_nop 4
	v_rcp_f32_e32 v0, v98
	s_nop 0
	v_mul_f32_e32 v82, v82, v0
	v_mul_f32_e32 v0, 0xbfb8aa3b, v84
	v_pk_mul_f32 v[66:67], v[66:67], v[82:83]
	v_exp_f32_e32 v82, v0
	v_mul_f32_e32 v0, 0xbfb8aa3b, v85
	v_exp_f32_e32 v83, v0
	v_cvt_pk_bf16_f32 v66, v66, v67
	v_pk_add_f32 v[82:83], v[82:83], 1.0 op_sel_hi:[1,0]
	s_nop 4
	v_rcp_f32_e32 v0, v83
	s_nop 0
	v_mul_f32_e32 v83, v85, v0
	s_nop 4
	v_rcp_f32_e32 v0, v82
	s_nop 0
	v_mul_f32_e32 v82, v84, v0
	v_pk_mul_f32 v[68:69], v[68:69], v[82:83]
	v_mul_f32_e32 v0, 0xbfb8aa3b, v86
	v_cvt_pk_bf16_f32 v67, v68, v69
	v_exp_f32_e32 v68, v0
	v_mul_f32_e32 v0, 0xbfb8aa3b, v87
	v_exp_f32_e32 v69, v0
	s_nop 0
	v_pk_add_f32 v[68:69], v[68:69], 1.0 op_sel_hi:[1,0]
	s_nop 4
	v_rcp_f32_e32 v0, v69
	s_nop 0
	v_mul_f32_e32 v69, v87, v0
	s_nop 4
	v_rcp_f32_e32 v0, v68
	s_nop 0
	v_mul_f32_e32 v68, v86, v0
	v_mul_f32_e32 v0, 0xbfb8aa3b, v88
	v_pk_mul_f32 v[68:69], v[70:71], v[68:69]
	v_exp_f32_e32 v70, v0
	v_mul_f32_e32 v0, 0xbfb8aa3b, v89
	v_exp_f32_e32 v71, v0
	v_cvt_pk_bf16_f32 v68, v68, v69
	s_nop 1
	v_permlane32_swap_b32_e32 v66, v68
	v_pk_add_f32 v[70:71], v[70:71], 1.0 op_sel_hi:[1,0]
	s_nop 4
	v_rcp_f32_e32 v0, v71
	s_nop 0
	v_mul_f32_e32 v71, v89, v0
	s_nop 4
	v_rcp_f32_e32 v0, v70
	s_nop 0
	v_mul_f32_e32 v70, v88, v0
	v_pk_mul_f32 v[70:71], v[72:73], v[70:71]
	v_mul_f32_e32 v0, 0xbfb8aa3b, v90
	v_cvt_pk_bf16_f32 v69, v70, v71
	s_nop 1
	v_permlane32_swap_b32_e32 v67, v69
	global_store_dwordx4 v[132:133], v[66:69], off offset:64
	s_nop 1
	v_exp_f32_e32 v66, v0
	v_mul_f32_e32 v0, 0xbfb8aa3b, v91
	v_exp_f32_e32 v67, v0
	s_nop 0
	v_pk_add_f32 v[66:67], v[66:67], 1.0 op_sel_hi:[1,0]
	s_nop 4
	v_rcp_f32_e32 v0, v67
	s_nop 0
	v_mul_f32_e32 v67, v91, v0
	s_nop 4
	v_rcp_f32_e32 v0, v66
	s_nop 0
	v_mul_f32_e32 v66, v90, v0
	v_mul_f32_e32 v0, 0xbfb8aa3b, v92
	v_exp_f32_e32 v68, v0
	v_mul_f32_e32 v0, 0xbfb8aa3b, v93
	v_exp_f32_e32 v69, v0
	v_pk_mul_f32 v[66:67], v[74:75], v[66:67]
	v_pk_add_f32 v[68:69], v[68:69], 1.0 op_sel_hi:[1,0]
	s_nop 2
	v_cvt_pk_bf16_f32 v66, v66, v67
	s_nop 4
	v_rcp_f32_e32 v0, v69
	s_nop 0
	v_mul_f32_e32 v69, v93, v0
	s_nop 4
	v_rcp_f32_e32 v0, v68
	s_nop 0
	v_mul_f32_e32 v68, v92, v0
	v_pk_mul_f32 v[68:69], v[76:77], v[68:69]
	v_mul_f32_e32 v0, 0xbfb8aa3b, v94
	v_cvt_pk_bf16_f32 v67, v68, v69
	v_exp_f32_e32 v68, v0
	v_mul_f32_e32 v0, 0xbfb8aa3b, v95
	v_exp_f32_e32 v69, v0
	s_nop 0
	v_pk_add_f32 v[68:69], v[68:69], 1.0 op_sel_hi:[1,0]
	s_nop 4
	v_rcp_f32_e32 v0, v69
	s_nop 0
	v_mul_f32_e32 v69, v95, v0
	s_nop 4
	v_rcp_f32_e32 v0, v68
	s_nop 0
	v_mul_f32_e32 v68, v94, v0
	v_mul_f32_e32 v0, 0xbfb8aa3b, v96
	v_exp_f32_e32 v70, v0
	v_mul_f32_e32 v0, 0xbfb8aa3b, v97
	v_exp_f32_e32 v71, v0
	v_pk_mul_f32 v[68:69], v[78:79], v[68:69]
	v_pk_add_f32 v[70:71], v[70:71], 1.0 op_sel_hi:[1,0]
	s_nop 2
	v_cvt_pk_bf16_f32 v68, v68, v69
	s_nop 1
	v_permlane32_swap_b32_e32 v66, v68
	s_nop 4
	v_rcp_f32_e32 v0, v71
	s_nop 0
	v_mul_f32_e32 v71, v97, v0
	s_nop 4
	v_rcp_f32_e32 v0, v70
	s_nop 0
	v_mul_f32_e32 v70, v96, v0
	v_pk_mul_f32 v[70:71], v[80:81], v[70:71]
	v_or_b32_e32 v0, 32, v134
	v_cvt_pk_bf16_f32 v69, v70, v71
	s_nop 1
	v_permlane32_swap_b32_e32 v67, v69
	global_store_dwordx4 v[132:133], v[66:69], off offset:96
	s_nop 1
	v_mad_i64_i32 v[66:67], s[6:7], v0, s8, v[130:131]
	v_mul_f32_e32 v0, 0xbfb8aa3b, v50
	v_exp_f32_e32 v68, v0
	v_mul_f32_e32 v0, 0xbfb8aa3b, v51
	v_exp_f32_e32 v69, v0
	s_nop 0
	v_pk_add_f32 v[68:69], v[68:69], 1.0 op_sel_hi:[1,0]
	s_nop 4
	v_rcp_f32_e32 v0, v69
	s_nop 0
	v_mul_f32_e32 v51, v51, v0
	s_nop 4
	v_rcp_f32_e32 v0, v68
	s_nop 0
	v_mul_f32_e32 v50, v50, v0
	v_mul_f32_e32 v0, 0xbfb8aa3b, v52
	v_pk_mul_f32 v[34:35], v[34:35], v[50:51]
	v_exp_f32_e32 v50, v0
	v_mul_f32_e32 v0, 0xbfb8aa3b, v53
	v_exp_f32_e32 v51, v0
	v_cvt_pk_bf16_f32 v34, v34, v35
	v_pk_add_f32 v[50:51], v[50:51], 1.0 op_sel_hi:[1,0]
	s_nop 4
	v_rcp_f32_e32 v0, v51
	s_nop 0
	v_mul_f32_e32 v51, v53, v0
	s_nop 4
	v_rcp_f32_e32 v0, v50
	s_nop 0
	v_mul_f32_e32 v50, v52, v0
	v_pk_mul_f32 v[36:37], v[36:37], v[50:51]
	v_mul_f32_e32 v0, 0xbfb8aa3b, v54
	v_cvt_pk_bf16_f32 v35, v36, v37
	v_exp_f32_e32 v36, v0
	v_mul_f32_e32 v0, 0xbfb8aa3b, v55
	v_exp_f32_e32 v37, v0
	s_nop 0
	v_pk_add_f32 v[36:37], v[36:37], 1.0 op_sel_hi:[1,0]
	s_nop 4
	v_rcp_f32_e32 v0, v37
	s_nop 0
	v_mul_f32_e32 v37, v55, v0
	s_nop 4
	v_rcp_f32_e32 v0, v36
	s_nop 0
	v_mul_f32_e32 v36, v54, v0
	v_mul_f32_e32 v0, 0xbfb8aa3b, v56
	v_pk_mul_f32 v[36:37], v[38:39], v[36:37]
	v_exp_f32_e32 v38, v0
	v_mul_f32_e32 v0, 0xbfb8aa3b, v57
	v_exp_f32_e32 v39, v0
	v_cvt_pk_bf16_f32 v36, v36, v37
	s_nop 1
	v_permlane32_swap_b32_e32 v34, v36
	v_pk_add_f32 v[38:39], v[38:39], 1.0 op_sel_hi:[1,0]
	s_nop 4
	v_rcp_f32_e32 v0, v39
	s_nop 0
	v_mul_f32_e32 v39, v57, v0
	s_nop 4
	v_rcp_f32_e32 v0, v38
	s_nop 0
	v_mul_f32_e32 v38, v56, v0
	v_pk_mul_f32 v[38:39], v[40:41], v[38:39]
	v_mul_f32_e32 v0, 0xbfb8aa3b, v58
	v_cvt_pk_bf16_f32 v37, v38, v39
	s_nop 1
	v_permlane32_swap_b32_e32 v35, v37
	global_store_dwordx4 v[66:67], v[34:37], off
	s_nop 1
	v_exp_f32_e32 v34, v0
	v_mul_f32_e32 v0, 0xbfb8aa3b, v59
	v_exp_f32_e32 v35, v0
	s_nop 0
	v_pk_add_f32 v[34:35], v[34:35], 1.0 op_sel_hi:[1,0]
	s_nop 4
	v_rcp_f32_e32 v0, v35
	s_nop 0
	v_mul_f32_e32 v35, v59, v0
	s_nop 4
	v_rcp_f32_e32 v0, v34
	s_nop 0
	v_mul_f32_e32 v34, v58, v0
	v_mul_f32_e32 v0, 0xbfb8aa3b, v60
	v_exp_f32_e32 v36, v0
	v_mul_f32_e32 v0, 0xbfb8aa3b, v61
	v_exp_f32_e32 v37, v0
	v_pk_mul_f32 v[34:35], v[42:43], v[34:35]
	v_pk_add_f32 v[36:37], v[36:37], 1.0 op_sel_hi:[1,0]
	s_nop 2
	v_cvt_pk_bf16_f32 v34, v34, v35
	s_nop 4
	v_rcp_f32_e32 v0, v37
	s_nop 0
	v_mul_f32_e32 v37, v61, v0
	s_nop 4
	v_rcp_f32_e32 v0, v36
	s_nop 0
	v_mul_f32_e32 v36, v60, v0
	v_pk_mul_f32 v[36:37], v[44:45], v[36:37]
	v_mul_f32_e32 v0, 0xbfb8aa3b, v62
	v_cvt_pk_bf16_f32 v35, v36, v37
	v_exp_f32_e32 v36, v0
	v_mul_f32_e32 v0, 0xbfb8aa3b, v63
	v_exp_f32_e32 v37, v0
	s_nop 0
	v_pk_add_f32 v[36:37], v[36:37], 1.0 op_sel_hi:[1,0]
	s_nop 4
	v_rcp_f32_e32 v0, v37
	s_nop 0
	v_mul_f32_e32 v37, v63, v0
	s_nop 4
	v_rcp_f32_e32 v0, v36
	s_nop 0
	v_mul_f32_e32 v36, v62, v0
	v_mul_f32_e32 v0, 0xbfb8aa3b, v64
	v_exp_f32_e32 v38, v0
	v_mul_f32_e32 v0, 0xbfb8aa3b, v65
	v_exp_f32_e32 v39, v0
	v_pk_mul_f32 v[36:37], v[46:47], v[36:37]
	v_pk_add_f32 v[38:39], v[38:39], 1.0 op_sel_hi:[1,0]
	s_nop 2
	v_cvt_pk_bf16_f32 v36, v36, v37
	s_nop 1
	v_permlane32_swap_b32_e32 v34, v36
	s_nop 4
	v_rcp_f32_e32 v0, v39
	s_nop 0
	v_mul_f32_e32 v39, v65, v0
	s_nop 4
	v_rcp_f32_e32 v0, v38
	s_nop 0
	v_mul_f32_e32 v38, v64, v0
	v_pk_mul_f32 v[38:39], v[48:49], v[38:39]
	v_mul_f32_e32 v0, 0xbfb8aa3b, v18
	v_cvt_pk_bf16_f32 v37, v38, v39
	s_nop 1
	v_permlane32_swap_b32_e32 v35, v37
	global_store_dwordx4 v[66:67], v[34:37], off offset:32
	s_nop 1
	v_exp_f32_e32 v34, v0
	v_mul_f32_e32 v0, 0xbfb8aa3b, v19
	v_exp_f32_e32 v35, v0
	s_nop 0
	v_pk_add_f32 v[34:35], v[34:35], 1.0 op_sel_hi:[1,0]
	s_nop 4
	v_rcp_f32_e32 v0, v35
	s_nop 0
	v_mul_f32_e32 v19, v19, v0
	s_nop 4
	v_rcp_f32_e32 v0, v34
	s_nop 0
	v_mul_f32_e32 v18, v18, v0
	v_mul_f32_e32 v0, 0xbfb8aa3b, v20
	v_pk_mul_f32 v[2:3], v[2:3], v[18:19]
	v_exp_f32_e32 v18, v0
	v_mul_f32_e32 v0, 0xbfb8aa3b, v21
	v_exp_f32_e32 v19, v0
	v_cvt_pk_bf16_f32 v2, v2, v3
	v_pk_add_f32 v[18:19], v[18:19], 1.0 op_sel_hi:[1,0]
	s_nop 4
	v_rcp_f32_e32 v0, v19
	s_nop 0
	v_mul_f32_e32 v19, v21, v0
	s_nop 4
	v_rcp_f32_e32 v0, v18
	s_nop 0
	v_mul_f32_e32 v18, v20, v0
	v_pk_mul_f32 v[4:5], v[4:5], v[18:19]
	v_mul_f32_e32 v0, 0xbfb8aa3b, v22
	v_cvt_pk_bf16_f32 v3, v4, v5
	v_exp_f32_e32 v4, v0
	v_mul_f32_e32 v0, 0xbfb8aa3b, v23
	v_exp_f32_e32 v5, v0
	s_nop 0
	v_pk_add_f32 v[4:5], v[4:5], 1.0 op_sel_hi:[1,0]
	s_nop 4
	v_rcp_f32_e32 v0, v5
	s_nop 0
	v_mul_f32_e32 v5, v23, v0
	s_nop 4
	v_rcp_f32_e32 v0, v4
	s_nop 0
	v_mul_f32_e32 v4, v22, v0
	v_mul_f32_e32 v0, 0xbfb8aa3b, v24
	v_pk_mul_f32 v[4:5], v[6:7], v[4:5]
	v_exp_f32_e32 v6, v0
	v_mul_f32_e32 v0, 0xbfb8aa3b, v25
	v_exp_f32_e32 v7, v0
	v_cvt_pk_bf16_f32 v4, v4, v5
	s_nop 1
	v_permlane32_swap_b32_e32 v2, v4
	v_pk_add_f32 v[6:7], v[6:7], 1.0 op_sel_hi:[1,0]
	s_nop 4
	v_rcp_f32_e32 v0, v7
	s_nop 0
	v_mul_f32_e32 v7, v25, v0
	s_nop 4
	v_rcp_f32_e32 v0, v6
	s_nop 0
	v_mul_f32_e32 v6, v24, v0
	v_pk_mul_f32 v[6:7], v[8:9], v[6:7]
	v_mul_f32_e32 v0, 0xbfb8aa3b, v26
	v_cvt_pk_bf16_f32 v5, v6, v7
	s_nop 1
	v_permlane32_swap_b32_e32 v3, v5
	global_store_dwordx4 v[66:67], v[2:5], off offset:64
	s_nop 1
	v_exp_f32_e32 v2, v0
	v_mul_f32_e32 v0, 0xbfb8aa3b, v27
	v_exp_f32_e32 v3, v0
	s_nop 0
	v_pk_add_f32 v[2:3], v[2:3], 1.0 op_sel_hi:[1,0]
	s_nop 4
	v_rcp_f32_e32 v0, v3
	s_nop 0
	v_mul_f32_e32 v3, v27, v0
	s_nop 4
	v_rcp_f32_e32 v0, v2
	s_nop 0
	v_mul_f32_e32 v2, v26, v0
	v_mul_f32_e32 v0, 0xbfb8aa3b, v28
	v_exp_f32_e32 v4, v0
	v_mul_f32_e32 v0, 0xbfb8aa3b, v29
	v_exp_f32_e32 v5, v0
	v_pk_mul_f32 v[2:3], v[10:11], v[2:3]
	v_pk_add_f32 v[4:5], v[4:5], 1.0 op_sel_hi:[1,0]
	s_nop 2
	v_cvt_pk_bf16_f32 v2, v2, v3
	s_nop 4
	v_rcp_f32_e32 v0, v5
	s_nop 0
	v_mul_f32_e32 v5, v29, v0
	s_nop 4
	v_rcp_f32_e32 v0, v4
	s_nop 0
	v_mul_f32_e32 v4, v28, v0
	v_pk_mul_f32 v[4:5], v[12:13], v[4:5]
	v_mul_f32_e32 v0, 0xbfb8aa3b, v30
	v_cvt_pk_bf16_f32 v3, v4, v5
	v_exp_f32_e32 v4, v0
	v_mul_f32_e32 v0, 0xbfb8aa3b, v31
	v_exp_f32_e32 v5, v0
	s_nop 0
	v_pk_add_f32 v[4:5], v[4:5], 1.0 op_sel_hi:[1,0]
	s_nop 4
	v_rcp_f32_e32 v0, v5
	s_nop 0
	v_mul_f32_e32 v5, v31, v0
	s_nop 4
	v_rcp_f32_e32 v0, v4
	s_nop 0
	v_mul_f32_e32 v4, v30, v0
	v_mul_f32_e32 v0, 0xbfb8aa3b, v32
	v_exp_f32_e32 v6, v0
	v_mul_f32_e32 v0, 0xbfb8aa3b, v33
	v_exp_f32_e32 v7, v0
	v_pk_mul_f32 v[4:5], v[14:15], v[4:5]
	v_pk_add_f32 v[6:7], v[6:7], 1.0 op_sel_hi:[1,0]
	s_nop 2
	v_cvt_pk_bf16_f32 v4, v4, v5
	s_nop 1
	v_permlane32_swap_b32_e32 v2, v4
	s_nop 4
	v_rcp_f32_e32 v0, v7
	s_nop 0
	v_mul_f32_e32 v7, v33, v0
	s_nop 1
	s_mov_b64 s[6:7], 0
	s_nop 4
	v_rcp_f32_e32 v0, v6
	s_nop 0
	v_mul_f32_e32 v6, v32, v0
	v_pk_mul_f32 v[6:7], v[16:17], v[6:7]
	s_nop 0
	v_cvt_pk_bf16_f32 v5, v6, v7
	s_nop 1
	v_permlane32_swap_b32_e32 v3, v5
	global_store_dwordx4 v[66:67], v[2:5], off offset:96

.LBB0_135:
	v_mul_f32_e32 v0, 0xbfb8aa3b, v114
	s_waitcnt vmcnt(2)
	v_exp_f32_e32 v158, v0
	v_mul_f32_e32 v0, 0xbfb8aa3b, v115
	v_exp_f32_e32 v159, v0
	v_mul_f32_e32 v0, 0xbfb8aa3b, v116
	v_exp_f32_e32 v156, v0
	v_mul_f32_e32 v0, 0xbfb8aa3b, v117
	v_exp_f32_e32 v157, v0
	v_mul_f32_e32 v0, 0xbfb8aa3b, v118
	v_exp_f32_e32 v154, v0
	v_mul_f32_e32 v0, 0xbfb8aa3b, v119
	v_exp_f32_e32 v155, v0
	v_mul_f32_e32 v0, 0xbfb8aa3b, v120
	v_exp_f32_e32 v152, v0
	v_mul_f32_e32 v0, 0xbfb8aa3b, v121
	v_exp_f32_e32 v153, v0
	v_mul_f32_e32 v0, 0xbfb8aa3b, v122
	v_exp_f32_e32 v150, v0
	v_mul_f32_e32 v0, 0xbfb8aa3b, v123
	v_exp_f32_e32 v151, v0
	v_mul_f32_e32 v0, 0xbfb8aa3b, v124
	v_exp_f32_e32 v148, v0
	v_mul_f32_e32 v0, 0xbfb8aa3b, v125
	v_exp_f32_e32 v149, v0
	v_mul_f32_e32 v0, 0xbfb8aa3b, v126
	v_exp_f32_e32 v146, v0
	v_mul_f32_e32 v0, 0xbfb8aa3b, v127
	v_exp_f32_e32 v147, v0
	v_mul_f32_e32 v0, 0xbfb8aa3b, v128
	v_exp_f32_e32 v128, v0
	v_mul_f32_e32 v0, 0xbfb8aa3b, v129
	v_exp_f32_e32 v129, v0
	v_mul_f32_e32 v0, 0xbfb8aa3b, v98
	v_exp_f32_e32 v126, v0
	v_mul_f32_e32 v0, 0xbfb8aa3b, v99
	v_exp_f32_e32 v127, v0
	v_mul_f32_e32 v0, 0xbfb8aa3b, v100
	v_exp_f32_e32 v124, v0
	v_mul_f32_e32 v0, 0xbfb8aa3b, v101
	v_exp_f32_e32 v125, v0
	v_mul_f32_e32 v0, 0xbfb8aa3b, v102
	v_exp_f32_e32 v122, v0
	v_mul_f32_e32 v0, 0xbfb8aa3b, v103
	v_exp_f32_e32 v123, v0
	v_mul_f32_e32 v0, 0xbfb8aa3b, v104
	v_exp_f32_e32 v120, v0
	v_mul_f32_e32 v0, 0xbfb8aa3b, v105
	v_exp_f32_e32 v121, v0
	v_mul_f32_e32 v0, 0xbfb8aa3b, v106
	v_exp_f32_e32 v118, v0
	v_mul_f32_e32 v0, 0xbfb8aa3b, v107
	v_exp_f32_e32 v119, v0
	v_mul_f32_e32 v0, 0xbfb8aa3b, v108
	v_exp_f32_e32 v116, v0
	v_mul_f32_e32 v0, 0xbfb8aa3b, v109
	v_exp_f32_e32 v117, v0
	v_mul_f32_e32 v0, 0xbfb8aa3b, v110
	v_exp_f32_e32 v114, v0
	v_mul_f32_e32 v0, 0xbfb8aa3b, v111
	v_exp_f32_e32 v115, v0
	v_mul_f32_e32 v0, 0xbfb8aa3b, v112
	v_exp_f32_e32 v110, v0
	v_mul_f32_e32 v0, 0xbfb8aa3b, v113
	v_exp_f32_e32 v111, v0
	v_mul_f32_e32 v0, 0xbfb8aa3b, v82
	v_exp_f32_e32 v108, v0
	v_mul_f32_e32 v0, 0xbfb8aa3b, v83
	v_exp_f32_e32 v109, v0
	v_mul_f32_e32 v0, 0xbfb8aa3b, v84
	v_exp_f32_e32 v106, v0
	v_mul_f32_e32 v0, 0xbfb8aa3b, v85
	v_exp_f32_e32 v107, v0
	v_mul_f32_e32 v0, 0xbfb8aa3b, v86
	v_exp_f32_e32 v104, v0
	v_mul_f32_e32 v0, 0xbfb8aa3b, v87
	v_exp_f32_e32 v105, v0
	v_mul_f32_e32 v0, 0xbfb8aa3b, v88
	v_exp_f32_e32 v102, v0
	v_mul_f32_e32 v0, 0xbfb8aa3b, v89
	v_exp_f32_e32 v103, v0
	v_mul_f32_e32 v0, 0xbfb8aa3b, v90
	v_exp_f32_e32 v100, v0
	v_mul_f32_e32 v0, 0xbfb8aa3b, v91
	v_exp_f32_e32 v101, v0
	v_mul_f32_e32 v0, 0xbfb8aa3b, v92
	v_exp_f32_e32 v98, v0
	v_mul_f32_e32 v0, 0xbfb8aa3b, v93
	v_exp_f32_e32 v99, v0
	v_mul_f32_e32 v0, 0xbfb8aa3b, v94
	v_exp_f32_e32 v92, v0
	v_mul_f32_e32 v0, 0xbfb8aa3b, v95
	v_exp_f32_e32 v93, v0
	v_mul_f32_e32 v0, 0xbfb8aa3b, v96
	v_exp_f32_e32 v90, v0
	v_mul_f32_e32 v0, 0xbfb8aa3b, v97
	v_exp_f32_e32 v91, v0
	v_mul_f32_e32 v0, 0xbfb8aa3b, v66
	v_exp_f32_e32 v88, v0
	v_mul_f32_e32 v0, 0xbfb8aa3b, v67
	v_exp_f32_e32 v89, v0
	v_mul_f32_e32 v0, 0xbfb8aa3b, v68
	v_exp_f32_e32 v86, v0
	v_mul_f32_e32 v0, 0xbfb8aa3b, v69
	v_exp_f32_e32 v87, v0
	v_mul_f32_e32 v0, 0xbfb8aa3b, v70
	v_exp_f32_e32 v84, v0
	v_mul_f32_e32 v0, 0xbfb8aa3b, v71
	v_exp_f32_e32 v85, v0
	v_mul_f32_e32 v0, 0xbfb8aa3b, v72
	v_exp_f32_e32 v82, v0
	v_mul_f32_e32 v0, 0xbfb8aa3b, v73
	v_exp_f32_e32 v83, v0
	v_mul_f32_e32 v0, 0xbfb8aa3b, v74
	v_exp_f32_e32 v72, v0
	v_mul_f32_e32 v0, 0xbfb8aa3b, v75
	v_exp_f32_e32 v73, v0
	v_mul_f32_e32 v0, 0xbfb8aa3b, v76
	v_exp_f32_e32 v70, v0
	v_mul_f32_e32 v0, 0xbfb8aa3b, v77
	v_exp_f32_e32 v71, v0
	v_mul_f32_e32 v0, 0xbfb8aa3b, v78
	v_exp_f32_e32 v68, v0
	v_mul_f32_e32 v0, 0xbfb8aa3b, v79
	v_exp_f32_e32 v69, v0
	v_mul_f32_e32 v0, 0xbfb8aa3b, v80
	v_exp_f32_e32 v66, v0
	v_mul_f32_e32 v0, 0xbfb8aa3b, v81
	v_pk_add_f32 v[74:75], v[158:159], 1.0 op_sel_hi:[1,0]
	v_exp_f32_e32 v67, v0
	s_nop 1
	v_pk_add_f32 v[114:115], v[114:115], 1.0 op_sel_hi:[1,0]
	v_pk_add_f32 v[110:111], v[110:111], 1.0 op_sel_hi:[1,0]
	v_pk_add_f32 v[108:109], v[108:109], 1.0 op_sel_hi:[1,0]
	s_nop 4
	v_rcp_f32_e32 v0, v75
	s_nop 0
	v_mul_f32_e32 v0, 1.0, v0
	s_nop 1
	v_pk_add_f32 v[106:107], v[106:107], 1.0 op_sel_hi:[1,0]
	v_pk_add_f32 v[104:105], v[104:105], 1.0 op_sel_hi:[1,0]
	v_pk_add_f32 v[102:103], v[102:103], 1.0 op_sel_hi:[1,0]
	s_nop 4
	v_rcp_f32_e32 v75, v74
	s_nop 0
	v_mul_f32_e32 v74, 1.0, v75
	v_cvt_pk_bf16_f32 v0, v74, v0
	v_pk_add_f32 v[74:75], v[156:157], 1.0 op_sel_hi:[1,0]
	v_pk_add_f32 v[100:101], v[100:101], 1.0 op_sel_hi:[1,0]
	s_nop 1
	v_pk_add_f32 v[98:99], v[98:99], 1.0 op_sel_hi:[1,0]
	v_pk_add_f32 v[92:93], v[92:93], 1.0 op_sel_hi:[1,0]
	v_pk_add_f32 v[90:91], v[90:91], 1.0 op_sel_hi:[1,0]
	s_nop 4
	v_rcp_f32_e32 v76, v75
	s_nop 0
	v_mul_f32_e32 v75, 1.0, v76
	s_nop 1
	v_pk_add_f32 v[88:89], v[88:89], 1.0 op_sel_hi:[1,0]
	v_pk_add_f32 v[86:87], v[86:87], 1.0 op_sel_hi:[1,0]
	v_pk_add_f32 v[84:85], v[84:85], 1.0 op_sel_hi:[1,0]
	s_nop 4
	v_rcp_f32_e32 v76, v74
	s_nop 0
	v_mul_f32_e32 v74, 1.0, v76
	v_pk_add_f32 v[76:77], v[154:155], 1.0 op_sel_hi:[1,0]
	v_cvt_pk_bf16_f32 v74, v74, v75
	s_nop 1
	v_pk_add_f32 v[82:83], v[82:83], 1.0 op_sel_hi:[1,0]
	v_pk_add_f32 v[72:73], v[72:73], 1.0 op_sel_hi:[1,0]
	v_pk_add_f32 v[70:71], v[70:71], 1.0 op_sel_hi:[1,0]
	s_nop 4
	v_rcp_f32_e32 v75, v77
	s_nop 0
	v_mul_f32_e32 v75, 1.0, v75
	s_nop 1
	v_pk_add_f32 v[68:69], v[68:69], 1.0 op_sel_hi:[1,0]
	v_pk_add_f32 v[66:67], v[66:67], 1.0 op_sel_hi:[1,0]
	s_add_i32 s27, s27, 1
	s_nop 4
	v_rcp_f32_e32 v77, v76
	s_nop 0
	v_mul_f32_e32 v76, 1.0, v77
	v_cvt_pk_bf16_f32 v75, v76, v75
	v_pk_add_f32 v[76:77], v[152:153], 1.0 op_sel_hi:[1,0]
	s_cmp_lg_u32 s27, 3
	s_nop 4
	v_rcp_f32_e32 v78, v77
	s_nop 0
	v_mul_f32_e32 v77, 1.0, v78
	s_nop 4
	v_rcp_f32_e32 v78, v76
	s_nop 0
	v_mul_f32_e32 v76, 1.0, v78
	v_pk_add_f32 v[78:79], v[150:151], 1.0 op_sel_hi:[1,0]
	v_cvt_pk_bf16_f32 v76, v76, v77
	s_nop 4
	v_rcp_f32_e32 v77, v79
	s_nop 0
	v_mul_f32_e32 v77, 1.0, v77
	s_nop 4
	v_rcp_f32_e32 v79, v78
	s_nop 0
	v_mul_f32_e32 v78, 1.0, v79
	v_cvt_pk_bf16_f32 v77, v78, v77
	v_pk_add_f32 v[78:79], v[148:149], 1.0 op_sel_hi:[1,0]
	s_nop 4
	v_rcp_f32_e32 v80, v79
	s_nop 0
	v_mul_f32_e32 v79, 1.0, v80
	s_nop 4
	v_rcp_f32_e32 v80, v78
	s_nop 0
	v_mul_f32_e32 v78, 1.0, v80
	v_pk_add_f32 v[80:81], v[146:147], 1.0 op_sel_hi:[1,0]
	v_cvt_pk_bf16_f32 v78, v78, v79
	s_nop 4
	v_rcp_f32_e32 v79, v81
	s_nop 0
	v_mul_f32_e32 v79, 1.0, v79
	s_nop 4
	v_rcp_f32_e32 v81, v80
	s_nop 0
	v_mul_f32_e32 v80, 1.0, v81
	v_cvt_pk_bf16_f32 v79, v80, v79
	v_pk_add_f32 v[80:81], v[128:129], 1.0 op_sel_hi:[1,0]
	s_nop 4
	v_rcp_f32_e32 v94, v81
	s_nop 0
	v_mul_f32_e32 v81, 1.0, v94
	s_nop 4
	v_rcp_f32_e32 v94, v80
	s_nop 0
	v_mul_f32_e32 v80, 1.0, v94
	v_pk_add_f32 v[94:95], v[126:127], 1.0 op_sel_hi:[1,0]
	v_cvt_pk_bf16_f32 v80, v80, v81
	s_nop 4
	v_rcp_f32_e32 v81, v95
	s_nop 0
	v_mul_f32_e32 v81, 1.0, v81
	s_nop 4
	v_rcp_f32_e32 v95, v94
	s_nop 0
	v_mul_f32_e32 v94, 1.0, v95
	v_cvt_pk_bf16_f32 v81, v94, v81
	v_pk_add_f32 v[94:95], v[124:125], 1.0 op_sel_hi:[1,0]
	s_nop 4
	v_rcp_f32_e32 v96, v95
	s_nop 0
	v_mul_f32_e32 v95, 1.0, v96
	s_nop 4
	v_rcp_f32_e32 v96, v94
	s_nop 0
	v_mul_f32_e32 v94, 1.0, v96
	v_pk_add_f32 v[96:97], v[122:123], 1.0 op_sel_hi:[1,0]
	v_cvt_pk_bf16_f32 v94, v94, v95
	s_nop 4
	v_rcp_f32_e32 v95, v97
	s_nop 0
	v_mul_f32_e32 v95, 1.0, v95
	s_nop 4
	v_rcp_f32_e32 v97, v96
	s_nop 0
	v_mul_f32_e32 v96, 1.0, v97
	v_cvt_pk_bf16_f32 v95, v96, v95
	v_pk_add_f32 v[96:97], v[120:121], 1.0 op_sel_hi:[1,0]
	s_nop 4
	v_rcp_f32_e32 v112, v97
	s_nop 0
	v_mul_f32_e32 v97, 1.0, v112
	s_nop 4
	v_rcp_f32_e32 v112, v96
	s_nop 0
	v_mul_f32_e32 v96, 1.0, v112
	v_pk_add_f32 v[112:113], v[118:119], 1.0 op_sel_hi:[1,0]
	v_cvt_pk_bf16_f32 v96, v96, v97
	s_nop 4
	v_rcp_f32_e32 v97, v113
	s_nop 0
	v_mul_f32_e32 v97, 1.0, v97
	s_nop 4
	v_rcp_f32_e32 v113, v112
	s_nop 0
	v_mul_f32_e32 v112, 1.0, v113
	v_cvt_pk_bf16_f32 v97, v112, v97
	v_pk_add_f32 v[112:113], v[116:117], 1.0 op_sel_hi:[1,0]
	s_nop 4
	v_rcp_f32_e32 v116, v113
	s_nop 0
	v_mul_f32_e32 v113, 1.0, v116
	s_nop 4
	v_rcp_f32_e32 v116, v112
	s_nop 0
	v_mul_f32_e32 v112, 1.0, v116
	v_cvt_pk_bf16_f32 v112, v112, v113
	s_nop 4
	v_rcp_f32_e32 v113, v115
	s_nop 0
	v_mul_f32_e32 v113, 1.0, v113
	s_nop 4
	v_rcp_f32_e32 v115, v114
	s_nop 0
	v_mul_f32_e32 v114, 1.0, v115
	v_cvt_pk_bf16_f32 v113, v114, v113
	s_nop 4
	v_rcp_f32_e32 v114, v111
	s_nop 0
	v_mul_f32_e32 v111, 1.0, v114
	s_nop 4
	v_rcp_f32_e32 v114, v110
	s_nop 0
	v_mul_f32_e32 v110, 1.0, v114
	v_cvt_pk_bf16_f32 v110, v110, v111
	s_nop 4
	v_rcp_f32_e32 v111, v109
	s_nop 0
	v_mul_f32_e32 v109, 1.0, v111
	s_nop 4
	v_rcp_f32_e32 v111, v108
	s_nop 0
	v_mul_f32_e32 v108, 1.0, v111
	v_cvt_pk_bf16_f32 v108, v108, v109
	s_nop 4
	v_rcp_f32_e32 v109, v107
	s_nop 0
	v_mul_f32_e32 v107, 1.0, v109
	s_nop 4
	v_rcp_f32_e32 v109, v106
	s_nop 0
	v_mul_f32_e32 v106, 1.0, v109
	v_cvt_pk_bf16_f32 v106, v106, v107
	s_nop 4
	v_rcp_f32_e32 v107, v105
	s_nop 0
	v_mul_f32_e32 v105, 1.0, v107
	s_nop 4
	v_rcp_f32_e32 v107, v104
	s_nop 0
	v_mul_f32_e32 v104, 1.0, v107
	v_cvt_pk_bf16_f32 v104, v104, v105
	s_nop 1
	v_and_b32_e32 v115, 0xffff0000, v144
	s_nop 4
	v_rcp_f32_e32 v105, v103
	s_nop 0
	v_mul_f32_e32 v103, 1.0, v105
	s_nop 4
	v_rcp_f32_e32 v105, v102
	s_nop 0
	v_mul_f32_e32 v102, 1.0, v105
	v_cvt_pk_bf16_f32 v102, v102, v103
	s_nop 1
	v_lshlrev_b32_e32 v114, 16, v144
	s_nop 4
	v_rcp_f32_e32 v103, v101
	s_nop 0
	v_mul_f32_e32 v101, 1.0, v103
	s_nop 4
	v_rcp_f32_e32 v103, v100
	s_nop 0
	v_mul_f32_e32 v100, 1.0, v103
	v_cvt_pk_bf16_f32 v100, v100, v101
	s_nop 4
	v_rcp_f32_e32 v101, v99
	s_nop 0
	v_mul_f32_e32 v99, 1.0, v101
	s_nop 4
	v_rcp_f32_e32 v101, v98
	s_nop 0
	v_mul_f32_e32 v98, 1.0, v101
	v_cvt_pk_bf16_f32 v98, v98, v99
	s_nop 4
	v_rcp_f32_e32 v99, v93
	s_nop 0
	v_mul_f32_e32 v93, 1.0, v99
	s_nop 4
	v_rcp_f32_e32 v99, v92
	s_nop 0
	v_mul_f32_e32 v92, 1.0, v99
	v_cvt_pk_bf16_f32 v92, v92, v93
	s_nop 4
	v_rcp_f32_e32 v93, v91
	s_nop 0
	v_mul_f32_e32 v91, 1.0, v93
	s_nop 4
	v_rcp_f32_e32 v93, v90
	s_nop 0
	v_mul_f32_e32 v90, 1.0, v93
	v_cvt_pk_bf16_f32 v90, v90, v91
	s_nop 4
	v_rcp_f32_e32 v91, v89
	s_nop 0
	v_mul_f32_e32 v89, 1.0, v91
	s_nop 4
	v_rcp_f32_e32 v91, v88
	s_nop 0
	v_mul_f32_e32 v88, 1.0, v91
	v_cvt_pk_bf16_f32 v88, v88, v89
	s_nop 4
	v_rcp_f32_e32 v89, v87
	s_nop 0
	v_mul_f32_e32 v87, 1.0, v89
	s_nop 4
	v_rcp_f32_e32 v89, v86
	s_nop 0
	v_mul_f32_e32 v86, 1.0, v89
	v_cvt_pk_bf16_f32 v86, v86, v87
	s_nop 4
	v_rcp_f32_e32 v87, v85
	s_nop 0
	v_mul_f32_e32 v85, 1.0, v87
	s_nop 4
	v_rcp_f32_e32 v87, v84
	s_nop 0
	v_mul_f32_e32 v84, 1.0, v87
	v_cvt_pk_bf16_f32 v84, v84, v85
	s_nop 4
	v_rcp_f32_e32 v85, v83
	s_nop 0
	v_mul_f32_e32 v83, 1.0, v85
	s_nop 4
	v_rcp_f32_e32 v85, v82
	s_nop 0
	v_mul_f32_e32 v82, 1.0, v85
	v_cvt_pk_bf16_f32 v82, v82, v83
	s_nop 4
	v_rcp_f32_e32 v83, v73
	s_nop 0
	v_mul_f32_e32 v73, 1.0, v83
	s_nop 4
	v_rcp_f32_e32 v83, v72
	s_nop 0
	v_mul_f32_e32 v72, 1.0, v83
	v_cvt_pk_bf16_f32 v72, v72, v73
	s_nop 4
	v_rcp_f32_e32 v73, v71
	s_nop 0
	v_mul_f32_e32 v71, 1.0, v73
	s_nop 4
	v_rcp_f32_e32 v73, v70
	s_nop 0
	v_mul_f32_e32 v70, 1.0, v73
	v_cvt_pk_bf16_f32 v70, v70, v71
	s_nop 4
	v_rcp_f32_e32 v71, v69
	s_nop 0
	v_mul_f32_e32 v69, 1.0, v71
	s_nop 4
	v_rcp_f32_e32 v71, v68
	s_nop 0
	v_mul_f32_e32 v68, 1.0, v71
	v_cvt_pk_bf16_f32 v68, v68, v69
	s_nop 4
	v_rcp_f32_e32 v69, v67
	s_nop 0
	v_mul_f32_e32 v67, 1.0, v69
	s_nop 4
	v_rcp_f32_e32 v69, v66
	s_nop 0
	v_mul_f32_e32 v66, 1.0, v69
	v_cvt_pk_bf16_f32 v69, v66, v67
	v_lshlrev_b32_e32 v66, 16, v0
	v_and_b32_e32 v67, 0xffff0000, v0
	v_pk_mul_f32 v[116:117], v[50:51], v[66:67]
	v_pk_fma_f32 v[50:51], v[50:51], v[66:67], v[114:115]
	v_lshlrev_b32_e32 v66, 16, v145
	v_cndmask_b32_e64 v0, v51, v117, s[0:1]
	v_cndmask_b32_e64 v50, v50, v116, s[0:1]
	v_cvt_pk_bf16_f32 v144, v50, v0
	v_lshlrev_b32_e32 v50, 16, v74
	v_and_b32_e32 v51, 0xffff0000, v74
	v_and_b32_e32 v67, 0xffff0000, v145
	v_pk_mul_f32 v[114:115], v[52:53], v[50:51]
	v_pk_fma_f32 v[50:51], v[52:53], v[50:51], v[66:67]
	v_lshlrev_b32_e32 v52, 16, v247
	v_cndmask_b32_e64 v0, v51, v115, s[0:1]
	v_cndmask_b32_e64 v50, v50, v114, s[0:1]
	v_cvt_pk_bf16_f32 v145, v50, v0
	v_lshlrev_b32_e32 v50, 16, v75
	v_and_b32_e32 v51, 0xffff0000, v75
	v_and_b32_e32 v53, 0xffff0000, v247
	v_pk_mul_f32 v[66:67], v[54:55], v[50:51]
	v_pk_fma_f32 v[50:51], v[54:55], v[50:51], v[52:53]
	v_lshlrev_b32_e32 v52, 16, v248
	v_cndmask_b32_e64 v0, v51, v67, s[0:1]
	v_cndmask_b32_e64 v50, v50, v66, s[0:1]
	v_cvt_pk_bf16_f32 v247, v50, v0
	v_lshlrev_b32_e32 v50, 16, v76
	v_and_b32_e32 v51, 0xffff0000, v76
	v_and_b32_e32 v53, 0xffff0000, v248
	v_pk_mul_f32 v[54:55], v[56:57], v[50:51]
	v_pk_fma_f32 v[50:51], v[56:57], v[50:51], v[52:53]
	v_lshlrev_b32_e32 v52, 16, v142
	v_cndmask_b32_e64 v0, v51, v55, s[0:1]
	v_cndmask_b32_e64 v50, v50, v54, s[0:1]
	v_cvt_pk_bf16_f32 v248, v50, v0
	v_lshlrev_b32_e32 v50, 16, v77
	v_and_b32_e32 v51, 0xffff0000, v77
	v_and_b32_e32 v53, 0xffff0000, v142
	v_pk_mul_f32 v[54:55], v[58:59], v[50:51]
	v_pk_fma_f32 v[50:51], v[58:59], v[50:51], v[52:53]
	v_lshlrev_b32_e32 v52, 16, v143
	v_cndmask_b32_e64 v0, v51, v55, s[0:1]
	v_cndmask_b32_e64 v50, v50, v54, s[0:1]
	v_cvt_pk_bf16_f32 v142, v50, v0
	v_lshlrev_b32_e32 v50, 16, v78
	v_and_b32_e32 v51, 0xffff0000, v78
	v_and_b32_e32 v53, 0xffff0000, v143
	v_pk_mul_f32 v[54:55], v[60:61], v[50:51]
	v_pk_fma_f32 v[50:51], v[60:61], v[50:51], v[52:53]
	v_lshlrev_b32_e32 v52, 16, v245
	v_cndmask_b32_e64 v0, v51, v55, s[0:1]
	v_cndmask_b32_e64 v50, v50, v54, s[0:1]
	v_cvt_pk_bf16_f32 v143, v50, v0
	v_lshlrev_b32_e32 v50, 16, v79
	v_and_b32_e32 v51, 0xffff0000, v79
	v_and_b32_e32 v53, 0xffff0000, v245
	v_pk_mul_f32 v[54:55], v[62:63], v[50:51]
	v_pk_fma_f32 v[50:51], v[62:63], v[50:51], v[52:53]
	v_lshlrev_b32_e32 v52, 16, v246
	v_cndmask_b32_e64 v0, v51, v55, s[0:1]
	v_cndmask_b32_e64 v50, v50, v54, s[0:1]
	v_cvt_pk_bf16_f32 v245, v50, v0
	v_lshlrev_b32_e32 v50, 16, v80
	v_and_b32_e32 v51, 0xffff0000, v80
	v_and_b32_e32 v53, 0xffff0000, v246
	v_pk_mul_f32 v[54:55], v[64:65], v[50:51]
	v_pk_fma_f32 v[50:51], v[64:65], v[50:51], v[52:53]
	v_lshlrev_b32_e32 v52, 16, v140
	v_cndmask_b32_e64 v0, v51, v55, s[0:1]
	v_cndmask_b32_e64 v50, v50, v54, s[0:1]
	v_cvt_pk_bf16_f32 v246, v50, v0
	v_lshlrev_b32_e32 v50, 16, v81
	v_and_b32_e32 v51, 0xffff0000, v81
	v_and_b32_e32 v53, 0xffff0000, v140
	v_pk_mul_f32 v[54:55], v[34:35], v[50:51]
	v_pk_fma_f32 v[34:35], v[34:35], v[50:51], v[52:53]
	v_lshlrev_b32_e32 v50, 16, v141
	v_cndmask_b32_e64 v0, v35, v55, s[0:1]
	v_cndmask_b32_e64 v34, v34, v54, s[0:1]
	v_cvt_pk_bf16_f32 v140, v34, v0
	v_lshlrev_b32_e32 v34, 16, v94
	v_and_b32_e32 v35, 0xffff0000, v94
	v_and_b32_e32 v51, 0xffff0000, v141
	v_pk_mul_f32 v[52:53], v[36:37], v[34:35]
	v_pk_fma_f32 v[34:35], v[36:37], v[34:35], v[50:51]
	v_lshlrev_b32_e32 v36, 16, v225
	v_cndmask_b32_e64 v0, v35, v53, s[0:1]
	v_cndmask_b32_e64 v34, v34, v52, s[0:1]
	v_cvt_pk_bf16_f32 v141, v34, v0
	v_lshlrev_b32_e32 v34, 16, v95
	v_and_b32_e32 v35, 0xffff0000, v95
	v_and_b32_e32 v37, 0xffff0000, v225
	v_pk_mul_f32 v[50:51], v[38:39], v[34:35]
	v_pk_fma_f32 v[34:35], v[38:39], v[34:35], v[36:37]
	v_lshlrev_b32_e32 v36, 16, v226
	v_cndmask_b32_e64 v0, v35, v51, s[0:1]
	v_cndmask_b32_e64 v34, v34, v50, s[0:1]
	v_cvt_pk_bf16_f32 v225, v34, v0
	v_lshlrev_b32_e32 v34, 16, v96
	v_and_b32_e32 v35, 0xffff0000, v96
	v_and_b32_e32 v37, 0xffff0000, v226
	v_pk_mul_f32 v[38:39], v[40:41], v[34:35]
	v_pk_fma_f32 v[34:35], v[40:41], v[34:35], v[36:37]
	v_lshlrev_b32_e32 v36, 16, v138
	v_cndmask_b32_e64 v0, v35, v39, s[0:1]
	v_cndmask_b32_e64 v34, v34, v38, s[0:1]
	v_cvt_pk_bf16_f32 v226, v34, v0
	v_lshlrev_b32_e32 v34, 16, v97
	v_and_b32_e32 v35, 0xffff0000, v97
	v_and_b32_e32 v37, 0xffff0000, v138
	v_pk_mul_f32 v[38:39], v[42:43], v[34:35]
	v_pk_fma_f32 v[34:35], v[42:43], v[34:35], v[36:37]
	v_lshlrev_b32_e32 v36, 16, v139
	v_cndmask_b32_e64 v0, v35, v39, s[0:1]
	v_cndmask_b32_e64 v34, v34, v38, s[0:1]
	v_cvt_pk_bf16_f32 v138, v34, v0
	v_lshlrev_b32_e32 v34, 16, v112
	v_and_b32_e32 v35, 0xffff0000, v112
	v_and_b32_e32 v37, 0xffff0000, v139
	v_pk_mul_f32 v[38:39], v[44:45], v[34:35]
	v_pk_fma_f32 v[34:35], v[44:45], v[34:35], v[36:37]
	v_lshlrev_b32_e32 v36, 16, v223
	v_cndmask_b32_e64 v0, v35, v39, s[0:1]
	v_cndmask_b32_e64 v34, v34, v38, s[0:1]
	v_cvt_pk_bf16_f32 v139, v34, v0
	v_lshlrev_b32_e32 v34, 16, v113
	v_and_b32_e32 v35, 0xffff0000, v113
	v_and_b32_e32 v37, 0xffff0000, v223
	v_pk_mul_f32 v[38:39], v[46:47], v[34:35]
	v_pk_fma_f32 v[34:35], v[46:47], v[34:35], v[36:37]
	v_lshlrev_b32_e32 v36, 16, v224
	v_cndmask_b32_e64 v0, v35, v39, s[0:1]
	v_cndmask_b32_e64 v34, v34, v38, s[0:1]
	v_cvt_pk_bf16_f32 v223, v34, v0
	v_lshlrev_b32_e32 v34, 16, v110
	v_and_b32_e32 v35, 0xffff0000, v110
	v_and_b32_e32 v37, 0xffff0000, v224
	v_pk_mul_f32 v[38:39], v[48:49], v[34:35]
	v_pk_fma_f32 v[34:35], v[48:49], v[34:35], v[36:37]
	v_lshlrev_b32_e32 v36, 16, v136
	v_cndmask_b32_e64 v0, v35, v39, s[0:1]
	v_cndmask_b32_e64 v34, v34, v38, s[0:1]
	v_cvt_pk_bf16_f32 v224, v34, v0
	v_lshlrev_b32_e32 v34, 16, v108
	v_and_b32_e32 v35, 0xffff0000, v108
	v_and_b32_e32 v37, 0xffff0000, v136
	v_pk_mul_f32 v[38:39], v[18:19], v[34:35]
	v_pk_fma_f32 v[18:19], v[18:19], v[34:35], v[36:37]
	v_lshlrev_b32_e32 v34, 16, v137
	v_cndmask_b32_e64 v0, v19, v39, s[0:1]
	v_cndmask_b32_e64 v18, v18, v38, s[0:1]
	v_cvt_pk_bf16_f32 v136, v18, v0
	v_lshlrev_b32_e32 v18, 16, v106
	v_and_b32_e32 v19, 0xffff0000, v106
	v_and_b32_e32 v35, 0xffff0000, v137
	v_pk_mul_f32 v[36:37], v[20:21], v[18:19]
	v_pk_fma_f32 v[18:19], v[20:21], v[18:19], v[34:35]
	v_lshlrev_b32_e32 v20, 16, v221
	v_cndmask_b32_e64 v0, v19, v37, s[0:1]
	v_cndmask_b32_e64 v18, v18, v36, s[0:1]
	v_cvt_pk_bf16_f32 v137, v18, v0
	v_lshlrev_b32_e32 v18, 16, v104
	v_and_b32_e32 v19, 0xffff0000, v104
	v_and_b32_e32 v21, 0xffff0000, v221
	v_pk_mul_f32 v[34:35], v[22:23], v[18:19]
	v_pk_fma_f32 v[18:19], v[22:23], v[18:19], v[20:21]
	v_lshlrev_b32_e32 v20, 16, v222
	v_cndmask_b32_e64 v0, v19, v35, s[0:1]
	v_cndmask_b32_e64 v18, v18, v34, s[0:1]
	v_cvt_pk_bf16_f32 v221, v18, v0
	v_lshlrev_b32_e32 v18, 16, v102
	v_and_b32_e32 v19, 0xffff0000, v102
	v_and_b32_e32 v21, 0xffff0000, v222
	v_pk_mul_f32 v[22:23], v[24:25], v[18:19]
	v_pk_fma_f32 v[18:19], v[24:25], v[18:19], v[20:21]
	v_lshlrev_b32_e32 v20, 16, v134
	v_cndmask_b32_e64 v0, v19, v23, s[0:1]
	v_cndmask_b32_e64 v18, v18, v22, s[0:1]
	v_cvt_pk_bf16_f32 v222, v18, v0
	v_lshlrev_b32_e32 v18, 16, v100
	v_and_b32_e32 v19, 0xffff0000, v100
	v_and_b32_e32 v21, 0xffff0000, v134
	v_pk_mul_f32 v[22:23], v[26:27], v[18:19]
	v_pk_fma_f32 v[18:19], v[26:27], v[18:19], v[20:21]
	v_lshlrev_b32_e32 v20, 16, v135
	v_cndmask_b32_e64 v0, v19, v23, s[0:1]
	v_cndmask_b32_e64 v18, v18, v22, s[0:1]
	v_cvt_pk_bf16_f32 v134, v18, v0
	v_lshlrev_b32_e32 v18, 16, v98
	v_and_b32_e32 v19, 0xffff0000, v98
	v_and_b32_e32 v21, 0xffff0000, v135
	v_pk_mul_f32 v[22:23], v[28:29], v[18:19]
	v_pk_fma_f32 v[18:19], v[28:29], v[18:19], v[20:21]
	v_lshlrev_b32_e32 v20, 16, v219
	v_cndmask_b32_e64 v0, v19, v23, s[0:1]
	v_cndmask_b32_e64 v18, v18, v22, s[0:1]
	v_cvt_pk_bf16_f32 v135, v18, v0
	v_lshlrev_b32_e32 v18, 16, v92
	v_and_b32_e32 v19, 0xffff0000, v92
	v_and_b32_e32 v21, 0xffff0000, v219
	v_pk_mul_f32 v[22:23], v[30:31], v[18:19]
	v_pk_fma_f32 v[18:19], v[30:31], v[18:19], v[20:21]
	v_lshlrev_b32_e32 v20, 16, v220
	v_cndmask_b32_e64 v0, v19, v23, s[0:1]
	v_cndmask_b32_e64 v18, v18, v22, s[0:1]
	v_cvt_pk_bf16_f32 v219, v18, v0
	v_lshlrev_b32_e32 v18, 16, v90
	v_and_b32_e32 v19, 0xffff0000, v90
	v_and_b32_e32 v21, 0xffff0000, v220
	v_pk_mul_f32 v[22:23], v[32:33], v[18:19]
	v_pk_fma_f32 v[18:19], v[32:33], v[18:19], v[20:21]
	v_lshlrev_b32_e32 v20, 16, v132
	v_cndmask_b32_e64 v0, v19, v23, s[0:1]
	v_cndmask_b32_e64 v18, v18, v22, s[0:1]
	v_cvt_pk_bf16_f32 v220, v18, v0
	v_lshlrev_b32_e32 v18, 16, v88
	v_and_b32_e32 v19, 0xffff0000, v88
	v_and_b32_e32 v21, 0xffff0000, v132
	v_pk_mul_f32 v[22:23], v[2:3], v[18:19]
	v_pk_fma_f32 v[2:3], v[2:3], v[18:19], v[20:21]
	v_lshlrev_b32_e32 v18, 16, v133
	v_cndmask_b32_e64 v0, v3, v23, s[0:1]
	v_cndmask_b32_e64 v2, v2, v22, s[0:1]
	v_cvt_pk_bf16_f32 v132, v2, v0
	v_lshlrev_b32_e32 v2, 16, v86
	v_and_b32_e32 v3, 0xffff0000, v86
	v_and_b32_e32 v19, 0xffff0000, v133
	v_pk_mul_f32 v[20:21], v[4:5], v[2:3]
	v_pk_fma_f32 v[2:3], v[4:5], v[2:3], v[18:19]
	v_lshlrev_b32_e32 v4, 16, v217
	v_cndmask_b32_e64 v0, v3, v21, s[0:1]
	v_cndmask_b32_e64 v2, v2, v20, s[0:1]
	v_cvt_pk_bf16_f32 v133, v2, v0
	v_lshlrev_b32_e32 v2, 16, v84
	v_and_b32_e32 v3, 0xffff0000, v84
	v_and_b32_e32 v5, 0xffff0000, v217
	v_pk_mul_f32 v[18:19], v[6:7], v[2:3]
	v_pk_fma_f32 v[2:3], v[6:7], v[2:3], v[4:5]
	v_lshlrev_b32_e32 v4, 16, v218
	v_cndmask_b32_e64 v0, v3, v19, s[0:1]
	v_cndmask_b32_e64 v2, v2, v18, s[0:1]
	v_cvt_pk_bf16_f32 v217, v2, v0
	v_lshlrev_b32_e32 v2, 16, v82
	v_and_b32_e32 v3, 0xffff0000, v82
	v_and_b32_e32 v5, 0xffff0000, v218
	v_pk_mul_f32 v[6:7], v[8:9], v[2:3]
	v_pk_fma_f32 v[2:3], v[8:9], v[2:3], v[4:5]
	v_lshlrev_b32_e32 v4, 16, v130
	v_cndmask_b32_e64 v0, v3, v7, s[0:1]
	v_cndmask_b32_e64 v2, v2, v6, s[0:1]
	v_cvt_pk_bf16_f32 v218, v2, v0
	v_lshlrev_b32_e32 v2, 16, v72
	v_and_b32_e32 v3, 0xffff0000, v72
	v_and_b32_e32 v5, 0xffff0000, v130
	v_pk_mul_f32 v[6:7], v[10:11], v[2:3]
	v_pk_fma_f32 v[2:3], v[10:11], v[2:3], v[4:5]
	v_lshlrev_b32_e32 v4, 16, v131
	v_cndmask_b32_e64 v0, v3, v7, s[0:1]
	v_cndmask_b32_e64 v2, v2, v6, s[0:1]
	v_cvt_pk_bf16_f32 v130, v2, v0
	v_lshlrev_b32_e32 v2, 16, v70
	v_and_b32_e32 v3, 0xffff0000, v70
	v_and_b32_e32 v5, 0xffff0000, v131
	v_pk_mul_f32 v[6:7], v[12:13], v[2:3]
	v_pk_fma_f32 v[2:3], v[12:13], v[2:3], v[4:5]
	v_lshlrev_b32_e32 v4, 16, v211
	v_cndmask_b32_e64 v0, v3, v7, s[0:1]
	v_cndmask_b32_e64 v2, v2, v6, s[0:1]
	v_cvt_pk_bf16_f32 v131, v2, v0
	v_lshlrev_b32_e32 v2, 16, v68
	v_and_b32_e32 v3, 0xffff0000, v68
	v_and_b32_e32 v5, 0xffff0000, v211
	v_pk_mul_f32 v[6:7], v[14:15], v[2:3]
	v_pk_fma_f32 v[2:3], v[14:15], v[2:3], v[4:5]
	v_lshlrev_b32_e32 v4, 16, v216
	v_cndmask_b32_e64 v0, v3, v7, s[0:1]
	v_cndmask_b32_e64 v2, v2, v6, s[0:1]
	v_cvt_pk_bf16_f32 v211, v2, v0
	v_lshlrev_b32_e32 v2, 16, v69
	v_and_b32_e32 v3, 0xffff0000, v69
	v_and_b32_e32 v5, 0xffff0000, v216
	v_pk_mul_f32 v[6:7], v[16:17], v[2:3]
	v_pk_fma_f32 v[2:3], v[16:17], v[2:3], v[4:5]
	s_nop 0
	v_cndmask_b32_e64 v0, v3, v7, s[0:1]
	v_cndmask_b32_e64 v2, v2, v6, s[0:1]
	v_cvt_pk_bf16_f32 v216, v2, v0
	s_cbranch_scc0 .LBB0_128

.LBB0_168:
	s_or_b64 exec, exec, s[12:13]
	v_lshlrev_b32_e32 v40, 16, v29
	v_and_b32_e32 v41, 0xffff0000, v29
	v_lshlrev_b32_e32 v42, 16, v33
	v_and_b32_e32 v43, 0xffff0000, v33
	v_pk_add_f32 v[40:41], v[40:41], v[42:43]
	v_lshlrev_b32_e32 v42, 16, v28
	v_and_b32_e32 v43, 0xffff0000, v28
	v_lshlrev_b32_e32 v28, 16, v32
	v_and_b32_e32 v29, 0xffff0000, v32
	v_pk_add_f32 v[28:29], v[42:43], v[28:29]
	v_mov_b32_e32 v32, v40
	v_mov_b32_e32 v33, v28
	v_pk_mul_f32 v[32:33], v[32:33], v[32:33]
	v_mov_b32_e32 v42, v41
	v_mov_b32_e32 v43, v29
	v_lshlrev_b32_e32 v44, 16, v12
	v_and_b32_e32 v12, 0xffff0000, v12
	v_pk_fma_f32 v[42:43], v[42:43], v[42:43], v[32:33]
	v_mul_f32_e32 v32, 0xbfb8aa3b, v44
	v_mul_f32_e32 v33, 0xbfb8aa3b, v12
	v_exp_f32_e32 v32, v32
	v_exp_f32_e32 v33, v33
	s_and_b64 s[0:1], exec, s[0:1]
	s_or_b64 s[10:11], s[0:1], s[10:11]
	v_lshl_add_u64 v[36:37], v[36:37], 0, s[8:9]
	v_pk_add_f32 v[32:33], v[32:33], 1.0 op_sel_hi:[1,0]
	s_nop 4
	v_rcp_f32_e32 v45, v33
	s_nop 0
	v_mul_f32_e32 v33, v12, v45
	s_nop 4
	v_rcp_f32_e32 v12, v32
	s_nop 0
	v_mul_f32_e32 v32, v44, v12
	v_lshlrev_b32_e32 v12, 16, v11
	v_lshlrev_b32_e32 v44, 16, v27
	v_and_b32_e32 v45, 0xffff0000, v27
	v_lshlrev_b32_e32 v46, 16, v31
	v_and_b32_e32 v47, 0xffff0000, v31
	v_and_b32_e32 v11, 0xffff0000, v11
	v_mul_f32_e32 v27, 0xbfb8aa3b, v12
	v_pk_add_f32 v[44:45], v[44:45], v[46:47]
	v_exp_f32_e32 v46, v27
	v_mul_f32_e32 v27, 0xbfb8aa3b, v11
	v_exp_f32_e32 v47, v27
	s_nop 0
	v_pk_add_f32 v[46:47], v[46:47], 1.0 op_sel_hi:[1,0]
	s_nop 4
	v_rcp_f32_e32 v27, v47
	s_nop 0
	v_mul_f32_e32 v47, v11, v27
	s_nop 1
	v_and_b32_e32 v53, 0xffff0000, v26
	s_nop 4
	v_rcp_f32_e32 v11, v46
	s_nop 0
	v_mul_f32_e32 v46, v12, v11
	v_lshlrev_b32_e32 v12, 16, v10
	v_and_b32_e32 v51, 0xffff0000, v10
	v_mul_f32_e32 v10, 0xbfb8aa3b, v12
	v_mul_f32_e32 v11, 0xbfb8aa3b, v51
	v_exp_f32_e32 v10, v10
	v_exp_f32_e32 v11, v11
	v_lshlrev_b32_e32 v52, 16, v26
	v_lshlrev_b32_e32 v26, 16, v30
	v_and_b32_e32 v27, 0xffff0000, v30
	v_pk_add_f32 v[26:27], v[52:53], v[26:27]
	v_mov_b32_e32 v31, v44
	v_mov_b32_e32 v30, v26
	v_pk_mul_f32 v[30:31], v[30:31], v[30:31]
	v_mov_b32_e32 v52, v27
	v_mov_b32_e32 v53, v45
	v_pk_add_f32 v[10:11], v[10:11], 1.0 op_sel_hi:[1,0]
	v_pk_fma_f32 v[30:31], v[52:53], v[52:53], v[30:31]
	s_nop 4
	v_rcp_f32_e32 v52, v11
	s_nop 0
	v_mul_f32_e32 v11, v51, v52
	s_nop 4
	v_rcp_f32_e32 v51, v10
	s_nop 0
	v_mul_f32_e32 v10, v12, v51
	v_add_f32_e32 v12, v30, v31
	v_add_f32_e32 v12, v43, v12
	v_add_f32_e32 v12, v42, v12
	ds_bpermute_b32 v30, v35, v12
	s_waitcnt lgkmcnt(0)
	v_add_f32_e32 v12, v12, v30
	ds_bpermute_b32 v30, v48, v12
	s_waitcnt lgkmcnt(0)
	v_add_f32_e32 v12, v12, v30
	ds_bpermute_b32 v30, v49, v12
	s_waitcnt lgkmcnt(0)
	v_add_f32_e32 v12, v12, v30
	ds_bpermute_b32 v30, v50, v12
	s_waitcnt lgkmcnt(0)
	v_add_f32_e32 v12, v12, v30
	v_fmamk_f32 v12, v12, 0x3c000000, v230
	v_cmp_gt_f32_e32 vcc, s95, v12
	v_mul_f32_e32 v30, 0x4b800000, v12
	s_nop 0
	v_cndmask_b32_e32 v12, v12, v30, vcc
	v_rsq_f32_e32 v12, v12
	s_nop 0
	v_mul_f32_e32 v30, 0x45800000, v12
	v_cndmask_b32_e32 v30, v12, v30, vcc
	v_pk_mul_f32 v[26:27], v[26:27], v[30:31] op_sel_hi:[1,0]
	s_nop 0
	v_pk_mul_f32 v[26:27], v[6:7], v[26:27]
	s_nop 0
	v_pk_mul_f32 v[10:11], v[10:11], v[26:27]
	v_pk_mul_f32 v[26:27], v[44:45], v[30:31] op_sel_hi:[1,0]
	v_cvt_pk_bf16_f32 v10, v10, v11
	v_pk_mul_f32 v[26:27], v[8:9], v[26:27]
	s_nop 0
	v_pk_mul_f32 v[26:27], v[46:47], v[26:27]
	s_nop 0
	v_cvt_pk_bf16_f32 v11, v26, v27
	v_pk_mul_f32 v[26:27], v[28:29], v[30:31] op_sel_hi:[1,0]
	v_lshlrev_b32_e32 v31, 16, v13
	v_pk_mul_f32 v[26:27], v[2:3], v[26:27]
	v_and_b32_e32 v13, 0xffff0000, v13
	v_pk_mul_f32 v[26:27], v[32:33], v[26:27]
	v_pk_mul_f32 v[28:29], v[40:41], v[30:31] op_sel_hi:[1,0]
	v_cvt_pk_bf16_f32 v12, v26, v27
	v_mul_f32_e32 v26, 0xbfb8aa3b, v31
	v_mul_f32_e32 v27, 0xbfb8aa3b, v13
	v_exp_f32_e32 v26, v26
	v_exp_f32_e32 v27, v27
	v_pk_mul_f32 v[28:29], v[4:5], v[28:29]
	v_pk_add_f32 v[26:27], v[26:27], 1.0 op_sel_hi:[1,0]
	s_nop 4
	v_rcp_f32_e32 v30, v27
	s_nop 0
	v_mul_f32_e32 v27, v13, v30
	s_nop 4
	v_rcp_f32_e32 v13, v26
	s_nop 0
	v_mul_f32_e32 v26, v31, v13
	v_pk_mul_f32 v[26:27], v[26:27], v[28:29]
	s_waitcnt vmcnt(1)
	v_mov_b64_e32 v[32:33], v[20:21]
	v_cvt_pk_bf16_f32 v13, v26, v27
	v_lshl_add_u64 v[26:27], v[38:39], 0, v[0:1]
	global_store_dwordx4 v[26:27], v[10:13], off
	v_mov_b64_e32 v[28:29], v[16:17]
	v_lshl_add_u64 v[38:39], v[38:39], 0, s[8:9]
	s_waitcnt vmcnt(0)
	v_mov_b64_e32 v[10:11], v[22:23]
	v_mov_b64_e32 v[26:27], v[14:15]
	v_mov_b64_e32 v[30:31], v[18:19]
	v_mov_b64_e32 v[12:13], v[24:25]
	s_andn2_b64 exec, exec, s[10:11]
	s_cbranch_execz .LBB0_171

.LBB0_208:
	v_sub_f32_e32 v96, v96, v157
	v_exp_f32_e32 v117, v96
	v_sub_f32_e32 v96, v97, v157
	v_exp_f32_e32 v118, v96
	v_sub_f32_e32 v96, v98, v157
	v_exp_f32_e32 v119, v96
	v_sub_f32_e32 v96, v99, v157
	v_exp_f32_e32 v122, v96
	v_sub_f32_e32 v96, v100, v157
	v_exp_f32_e32 v100, v96
	v_sub_f32_e32 v96, v101, v157
	v_exp_f32_e32 v101, v96
	v_sub_f32_e32 v96, v102, v157
	v_exp_f32_e32 v102, v96
	v_sub_f32_e32 v96, v103, v157
	v_exp_f32_e32 v103, v96
	v_cvt_pk_bf16_f32 v96, v117, v118
	v_cvt_pk_bf16_f32 v97, v119, v122
	v_cvt_pk_bf16_f32 v98, v100, v101
	v_cvt_pk_bf16_f32 v99, v102, v103
	v_sub_f32_e32 v80, v80, v157
	v_sub_f32_e32 v83, v83, v157
	v_mfma_f32_32x32x16_bf16 v[48:63], v[2:5], v[96:99], v[48:63]
	v_sub_f32_e32 v2, v104, v157
	v_exp_f32_e32 v104, v2
	v_sub_f32_e32 v2, v105, v157
	v_exp_f32_e32 v105, v2
	v_sub_f32_e32 v2, v106, v157
	v_exp_f32_e32 v106, v2
	v_sub_f32_e32 v2, v107, v157
	v_exp_f32_e32 v107, v2
	v_sub_f32_e32 v2, v108, v157
	v_exp_f32_e32 v108, v2
	v_sub_f32_e32 v2, v109, v157
	v_exp_f32_e32 v109, v2
	ds_read2_b64 v[2:5], v121 offset0:132 offset1:134
	v_mfma_f32_32x32x16_bf16 v[64:79], v[6:9], v[96:99], v[64:79]
	v_sub_f32_e32 v6, v110, v157
	v_cvt_pk_bf16_f32 v7, v106, v107
	v_cvt_pk_bf16_f32 v8, v108, v109
	v_sub_f32_e32 v86, v86, v157
	v_exp_f32_e32 v80, v80
	v_exp_f32_e32 v83, v83
	v_exp_f32_e32 v86, v86
	v_mfma_f32_32x32x16_bf16 v[32:47], v[112:115], v[96:99], v[32:47]
	s_waitcnt lgkmcnt(1)
	v_mfma_f32_32x32x16_bf16 v[16:31], v[10:13], v[96:99], v[16:31]
	v_exp_f32_e32 v96, v6
	v_sub_f32_e32 v6, v111, v157
	v_exp_f32_e32 v97, v6
	v_cvt_pk_bf16_f32 v6, v104, v105
	ds_read2_b64 v[10:13], v116 offset0:196 offset1:198
	v_cvt_pk_bf16_f32 v9, v96, v97
	s_waitcnt lgkmcnt(1)
	s_nop 0
	v_mfma_f32_32x32x16_bf16 v[64:79], v[2:5], v[6:9], v[64:79]
	ds_read2_b64 v[2:5], v120 offset0:164 offset1:166
	s_waitcnt lgkmcnt(0)
	v_mfma_f32_32x32x16_bf16 v[48:63], v[2:5], v[6:9], v[48:63]
	v_sub_f32_e32 v2, v81, v157
	v_exp_f32_e32 v81, v2
	v_sub_f32_e32 v2, v82, v157
	v_exp_f32_e32 v82, v2
	ds_read2_b64 v[2:5], v15 offset0:228 offset1:230
	v_mfma_f32_32x32x16_bf16 v[32:47], v[10:13], v[6:9], v[32:47]
	v_sub_f32_e32 v10, v84, v157
	v_exp_f32_e32 v84, v10
	v_sub_f32_e32 v10, v85, v157
	v_exp_f32_e32 v85, v10
	ds_read2_b64 v[10:13], v121 offset0:136 offset1:138
	s_waitcnt lgkmcnt(1)
	v_mfma_f32_32x32x16_bf16 v[16:31], v[2:5], v[6:9], v[16:31]
	v_sub_f32_e32 v2, v87, v157
	v_exp_f32_e32 v87, v2
	ds_read2_b64 v[6:9], v120 offset0:168 offset1:170
	v_cvt_pk_bf16_f32 v2, v80, v81
	v_cvt_pk_bf16_f32 v3, v82, v83
	v_cvt_pk_bf16_f32 v4, v84, v85
	v_cvt_pk_bf16_f32 v5, v86, v87
	s_waitcnt lgkmcnt(1)
	s_nop 0
	v_mfma_f32_32x32x16_bf16 v[64:79], v[10:13], v[2:5], v[64:79]
	v_add_f32_e32 v10, 0, v117
	v_add_f32_e32 v10, v118, v10
	v_add_f32_e32 v98, v119, v10
	v_sub_f32_e32 v10, v88, v157
	v_exp_f32_e32 v88, v10
	ds_read2_b64 v[10:13], v116 offset0:200 offset1:202
	s_waitcnt lgkmcnt(1)
	v_mfma_f32_32x32x16_bf16 v[48:63], v[6:9], v[2:5], v[48:63]
	v_sub_f32_e32 v6, v89, v157
	v_exp_f32_e32 v89, v6
	v_sub_f32_e32 v6, v90, v157
	v_exp_f32_e32 v90, v6
	v_sub_f32_e32 v6, v91, v157
	v_exp_f32_e32 v91, v6
	ds_read2_b64 v[6:9], v15 offset0:232 offset1:234
	s_waitcnt lgkmcnt(1)
	v_mfma_f32_32x32x16_bf16 v[32:47], v[10:13], v[2:5], v[32:47]
	v_sub_f32_e32 v10, v92, v157
	v_exp_f32_e32 v92, v10
	v_sub_f32_e32 v10, v93, v157
	v_exp_f32_e32 v93, v10
	v_sub_f32_e32 v10, v94, v157
	v_exp_f32_e32 v94, v10
	ds_read2_b64 v[10:13], v121 offset0:140 offset1:142
	s_waitcnt lgkmcnt(1)
	v_mfma_f32_32x32x16_bf16 v[16:31], v[6:9], v[2:5], v[16:31]
	v_sub_f32_e32 v2, v95, v157
	v_exp_f32_e32 v95, v2
	ds_read2_b64 v[2:5], v120 offset0:172 offset1:174
	v_cvt_pk_bf16_f32 v6, v88, v89
	v_cvt_pk_bf16_f32 v7, v90, v91
	v_cvt_pk_bf16_f32 v8, v92, v93
	v_cvt_pk_bf16_f32 v9, v94, v95
	s_waitcnt lgkmcnt(1)
	s_nop 0
	v_mfma_f32_32x32x16_bf16 v[64:79], v[10:13], v[6:9], v[64:79]
	v_add_f32_e32 v10, v122, v98
	v_add_f32_e32 v10, v100, v10
	v_add_f32_e32 v10, v101, v10
	v_add_f32_e32 v10, v102, v10
	v_add_f32_e32 v10, v103, v10
	v_add_f32_e32 v98, v104, v10
	ds_read2_b64 v[10:13], v116 offset0:204 offset1:206
	s_waitcnt lgkmcnt(1)
	v_mfma_f32_32x32x16_bf16 v[48:63], v[2:5], v[6:9], v[48:63]
	v_add_f32_e32 v2, v105, v98
	v_add_f32_e32 v2, v106, v2
	v_add_f32_e32 v2, v107, v2
	v_add_f32_e32 v2, v108, v2
	v_add_f32_e32 v2, v109, v2
	v_add_f32_e32 v2, v96, v2
	v_add_f32_e32 v2, v97, v2
	v_add_f32_e32 v2, v80, v2
	v_add_f32_e32 v2, v81, v2
	v_add_f32_e32 v2, v82, v2
	v_add_f32_e32 v2, v83, v2
	v_add_f32_e32 v2, v84, v2
	v_add_f32_e32 v2, v85, v2
	v_add_f32_e32 v2, v86, v2
	v_add_f32_e32 v2, v87, v2
	v_add_f32_e32 v2, v88, v2
	v_add_f32_e32 v2, v89, v2
	v_add_f32_e32 v2, v90, v2
	v_add_f32_e32 v2, v91, v2
	v_add_f32_e32 v2, v92, v2
	v_add_f32_e32 v2, v93, v2
	v_add_f32_e32 v2, v94, v2
	s_waitcnt lgkmcnt(0)
	v_mfma_f32_32x32x16_bf16 v[32:47], v[10:13], v[6:9], v[32:47]
	v_add_f32_e32 v10, v95, v2
	v_fmac_f32_e32 v10, v14, v0
	ds_bpermute_b32 v0, v149, v10
	ds_read2_b64 v[2:5], v15 offset0:236 offset1:238
	s_waitcnt lgkmcnt(0)
	s_barrier
	s_waitcnt lgkmcnt(1)
	v_add_f32_e32 v0, v10, v0
	s_nop 1
	s_waitcnt lgkmcnt(0)
	v_mfma_f32_32x32x16_bf16 v[16:31], v[2:5], v[6:9], v[16:31]
	v_cmp_ne_u32_e64 s[0:1], 0, v153
	s_nop 4
	v_rcp_f32_e32 v2, v0
	s_nop 0
	v_mul_f32_e32 v80, 1.0, v2
	v_lshlrev_b32_e32 v0, 14, v162
	v_lshlrev_b32_e32 v2, 2, v155
	v_cmp_eq_u32_e32 vcc, 0, v153
	v_add3_u32 v0, 0, v0, v2
	s_and_saveexec_b64 s[4:5], s[0:1]
	s_cbranch_execz .LBB0_210
	v_mul_f32_e32 v2, v64, v80
	v_mul_f32_e32 v3, v65, v80
	ds_write2st64_b32 v0, v2, v3 offset1:1
	v_mul_f32_e32 v2, v66, v80
	v_mul_f32_e32 v3, v67, v80
	ds_write2st64_b32 v0, v2, v3 offset0:2 offset1:3
	v_mul_f32_e32 v2, v68, v80
	v_mul_f32_e32 v3, v69, v80
	ds_write2st64_b32 v0, v2, v3 offset0:4 offset1:5
	v_mul_f32_e32 v2, v70, v80
	v_mul_f32_e32 v3, v71, v80
	ds_write2st64_b32 v0, v2, v3 offset0:6 offset1:7
	v_mul_f32_e32 v2, v72, v80
	v_mul_f32_e32 v3, v73, v80
	ds_write2st64_b32 v0, v2, v3 offset0:8 offset1:9
	v_mul_f32_e32 v2, v74, v80
	v_mul_f32_e32 v3, v75, v80
	ds_write2st64_b32 v0, v2, v3 offset0:10 offset1:11
	v_mul_f32_e32 v2, v76, v80
	v_mul_f32_e32 v3, v77, v80
	ds_write2st64_b32 v0, v2, v3 offset0:12 offset1:13
	v_mul_f32_e32 v2, v78, v80
	v_mul_f32_e32 v3, v79, v80
	ds_write2st64_b32 v0, v2, v3 offset0:14 offset1:15
	v_mul_f32_e32 v2, v48, v80
	v_mul_f32_e32 v3, v49, v80
	ds_write2st64_b32 v0, v2, v3 offset0:16 offset1:17
	v_mul_f32_e32 v2, v50, v80
	v_mul_f32_e32 v3, v51, v80
	ds_write2st64_b32 v0, v2, v3 offset0:18 offset1:19
	v_mul_f32_e32 v2, v52, v80
	v_mul_f32_e32 v3, v53, v80
	ds_write2st64_b32 v0, v2, v3 offset0:20 offset1:21
	v_mul_f32_e32 v2, v54, v80
	v_mul_f32_e32 v3, v55, v80
	ds_write2st64_b32 v0, v2, v3 offset0:22 offset1:23
	v_mul_f32_e32 v2, v56, v80
	v_mul_f32_e32 v3, v57, v80
	ds_write2st64_b32 v0, v2, v3 offset0:24 offset1:25
	v_mul_f32_e32 v2, v58, v80
	v_mul_f32_e32 v3, v59, v80
	ds_write2st64_b32 v0, v2, v3 offset0:26 offset1:27
	v_mul_f32_e32 v2, v60, v80
	v_mul_f32_e32 v3, v61, v80
	ds_write2st64_b32 v0, v2, v3 offset0:28 offset1:29
	v_mul_f32_e32 v2, v62, v80
	v_mul_f32_e32 v3, v63, v80
	ds_write2st64_b32 v0, v2, v3 offset0:30 offset1:31
	v_mul_f32_e32 v2, v32, v80
	v_mul_f32_e32 v3, v33, v80
	ds_write2st64_b32 v0, v2, v3 offset0:32 offset1:33
	v_mul_f32_e32 v2, v34, v80
	v_mul_f32_e32 v3, v35, v80
	ds_write2st64_b32 v0, v2, v3 offset0:34 offset1:35
	v_mul_f32_e32 v2, v36, v80
	v_mul_f32_e32 v3, v37, v80
	ds_write2st64_b32 v0, v2, v3 offset0:36 offset1:37
	v_mul_f32_e32 v2, v38, v80
	v_mul_f32_e32 v3, v39, v80
	ds_write2st64_b32 v0, v2, v3 offset0:38 offset1:39
	v_mul_f32_e32 v2, v40, v80
	v_mul_f32_e32 v3, v41, v80
	ds_write2st64_b32 v0, v2, v3 offset0:40 offset1:41
	v_mul_f32_e32 v2, v42, v80
	v_mul_f32_e32 v3, v43, v80
	ds_write2st64_b32 v0, v2, v3 offset0:42 offset1:43
	v_mul_f32_e32 v2, v44, v80
	v_mul_f32_e32 v3, v45, v80
	ds_write2st64_b32 v0, v2, v3 offset0:44 offset1:45
	v_mul_f32_e32 v2, v46, v80
	v_mul_f32_e32 v3, v47, v80
	ds_write2st64_b32 v0, v2, v3 offset0:46 offset1:47
	v_mul_f32_e32 v2, v16, v80
	v_mul_f32_e32 v3, v17, v80
	ds_write2st64_b32 v0, v2, v3 offset0:48 offset1:49
	v_mul_f32_e32 v2, v18, v80
	v_mul_f32_e32 v3, v19, v80
	ds_write2st64_b32 v0, v2, v3 offset0:50 offset1:51
	v_mul_f32_e32 v2, v20, v80
	v_mul_f32_e32 v3, v21, v80
	ds_write2st64_b32 v0, v2, v3 offset0:52 offset1:53
	v_mul_f32_e32 v2, v22, v80
	v_mul_f32_e32 v3, v23, v80
	ds_write2st64_b32 v0, v2, v3 offset0:54 offset1:55
	v_mul_f32_e32 v2, v24, v80
	v_mul_f32_e32 v3, v25, v80
	ds_write2st64_b32 v0, v2, v3 offset0:56 offset1:57
	v_mul_f32_e32 v2, v26, v80
	v_mul_f32_e32 v3, v27, v80
	ds_write2st64_b32 v0, v2, v3 offset0:58 offset1:59
	v_mul_f32_e32 v2, v28, v80
	v_mul_f32_e32 v3, v29, v80
	ds_write2st64_b32 v0, v2, v3 offset0:60 offset1:61
	v_mul_f32_e32 v2, v30, v80
	v_mul_f32_e32 v3, v31, v80
	ds_write2st64_b32 v0, v2, v3 offset0:62 offset1:63

.LBB0_224:
	v_sub_f32_e32 v96, v96, v157
	v_exp_f32_e32 v117, v96
	v_sub_f32_e32 v96, v97, v157
	v_exp_f32_e32 v118, v96
	v_sub_f32_e32 v96, v98, v157
	v_exp_f32_e32 v119, v96
	v_sub_f32_e32 v96, v99, v157
	v_exp_f32_e32 v122, v96
	v_sub_f32_e32 v96, v100, v157
	v_exp_f32_e32 v100, v96
	v_sub_f32_e32 v96, v101, v157
	v_exp_f32_e32 v101, v96
	v_sub_f32_e32 v96, v102, v157
	v_exp_f32_e32 v102, v96
	v_sub_f32_e32 v96, v103, v157
	v_exp_f32_e32 v103, v96
	v_cvt_pk_bf16_f32 v96, v117, v118
	v_cvt_pk_bf16_f32 v97, v119, v122
	v_cvt_pk_bf16_f32 v98, v100, v101
	v_cvt_pk_bf16_f32 v99, v102, v103
	v_sub_f32_e32 v80, v80, v157
	v_sub_f32_e32 v83, v83, v157
	v_mfma_f32_32x32x16_bf16 v[48:63], v[2:5], v[96:99], v[48:63]
	v_sub_f32_e32 v2, v104, v157
	v_exp_f32_e32 v104, v2
	v_sub_f32_e32 v2, v105, v157
	v_exp_f32_e32 v105, v2
	v_sub_f32_e32 v2, v106, v157
	v_exp_f32_e32 v106, v2
	v_sub_f32_e32 v2, v107, v157
	v_exp_f32_e32 v107, v2
	v_sub_f32_e32 v2, v108, v157
	v_exp_f32_e32 v108, v2
	v_sub_f32_e32 v2, v109, v157
	v_exp_f32_e32 v109, v2
	ds_read_b128 v[2:5], v195 offset:17440
	v_mfma_f32_32x32x16_bf16 v[64:79], v[6:9], v[96:99], v[64:79]
	v_sub_f32_e32 v6, v110, v157
	v_cvt_pk_bf16_f32 v7, v106, v107
	v_cvt_pk_bf16_f32 v8, v108, v109
	v_sub_f32_e32 v86, v86, v157
	v_exp_f32_e32 v80, v80
	v_exp_f32_e32 v83, v83
	v_exp_f32_e32 v86, v86
	v_mfma_f32_32x32x16_bf16 v[32:47], v[112:115], v[96:99], v[32:47]
	s_waitcnt lgkmcnt(1)
	v_mfma_f32_32x32x16_bf16 v[16:31], v[10:13], v[96:99], v[16:31]
	v_exp_f32_e32 v96, v6
	v_sub_f32_e32 v6, v111, v157
	v_exp_f32_e32 v97, v6
	v_cvt_pk_bf16_f32 v6, v104, v105
	ds_read_b128 v[10:13], v195 offset:26656
	v_cvt_pk_bf16_f32 v9, v96, v97
	s_waitcnt lgkmcnt(1)
	s_nop 0
	v_mfma_f32_32x32x16_bf16 v[64:79], v[2:5], v[6:9], v[64:79]
	ds_read_b128 v[2:5], v195 offset:22048
	s_waitcnt lgkmcnt(0)
	v_mfma_f32_32x32x16_bf16 v[48:63], v[2:5], v[6:9], v[48:63]
	v_sub_f32_e32 v2, v81, v157
	v_exp_f32_e32 v81, v2
	v_sub_f32_e32 v2, v82, v157
	v_exp_f32_e32 v82, v2
	ds_read_b128 v[2:5], v195 offset:31264
	v_mfma_f32_32x32x16_bf16 v[32:47], v[10:13], v[6:9], v[32:47]
	v_sub_f32_e32 v10, v84, v157
	v_exp_f32_e32 v84, v10
	v_sub_f32_e32 v10, v85, v157
	v_exp_f32_e32 v85, v10
	ds_read_b128 v[10:13], v195 offset:17472
	s_waitcnt lgkmcnt(1)
	v_mfma_f32_32x32x16_bf16 v[16:31], v[2:5], v[6:9], v[16:31]
	v_sub_f32_e32 v2, v87, v157
	v_exp_f32_e32 v87, v2
	ds_read_b128 v[6:9], v195 offset:22080
	v_cvt_pk_bf16_f32 v2, v80, v81
	v_cvt_pk_bf16_f32 v3, v82, v83
	v_cvt_pk_bf16_f32 v4, v84, v85
	v_cvt_pk_bf16_f32 v5, v86, v87
	s_waitcnt lgkmcnt(1)
	s_nop 0
	v_mfma_f32_32x32x16_bf16 v[64:79], v[10:13], v[2:5], v[64:79]
	v_add_f32_e32 v10, 0, v117
	v_add_f32_e32 v10, v118, v10
	v_add_f32_e32 v98, v119, v10
	v_sub_f32_e32 v10, v88, v157
	v_exp_f32_e32 v88, v10
	ds_read_b128 v[10:13], v195 offset:26688
	s_waitcnt lgkmcnt(1)
	v_mfma_f32_32x32x16_bf16 v[48:63], v[6:9], v[2:5], v[48:63]
	v_sub_f32_e32 v6, v89, v157
	v_exp_f32_e32 v89, v6
	v_sub_f32_e32 v6, v90, v157
	v_exp_f32_e32 v90, v6
	v_sub_f32_e32 v6, v91, v157
	v_exp_f32_e32 v91, v6
	ds_read_b128 v[6:9], v195 offset:31296
	s_waitcnt lgkmcnt(1)
	v_mfma_f32_32x32x16_bf16 v[32:47], v[10:13], v[2:5], v[32:47]
	v_sub_f32_e32 v10, v92, v157
	v_exp_f32_e32 v92, v10
	v_sub_f32_e32 v10, v93, v157
	v_exp_f32_e32 v93, v10
	v_sub_f32_e32 v10, v94, v157
	v_exp_f32_e32 v94, v10
	ds_read_b128 v[10:13], v195 offset:17504
	s_waitcnt lgkmcnt(1)
	v_mfma_f32_32x32x16_bf16 v[16:31], v[6:9], v[2:5], v[16:31]
	v_sub_f32_e32 v2, v95, v157
	v_exp_f32_e32 v95, v2
	ds_read_b128 v[2:5], v195 offset:22112
	v_cvt_pk_bf16_f32 v6, v88, v89
	v_cvt_pk_bf16_f32 v7, v90, v91
	v_cvt_pk_bf16_f32 v8, v92, v93
	v_cvt_pk_bf16_f32 v9, v94, v95
	s_waitcnt lgkmcnt(1)
	s_nop 0
	v_mfma_f32_32x32x16_bf16 v[64:79], v[10:13], v[6:9], v[64:79]
	v_add_f32_e32 v10, v122, v98
	v_add_f32_e32 v10, v100, v10
	v_add_f32_e32 v10, v101, v10
	v_add_f32_e32 v10, v102, v10
	v_add_f32_e32 v10, v103, v10
	v_add_f32_e32 v98, v104, v10
	ds_read_b128 v[10:13], v195 offset:26720
	s_waitcnt lgkmcnt(1)
	v_mfma_f32_32x32x16_bf16 v[48:63], v[2:5], v[6:9], v[48:63]
	v_add_f32_e32 v2, v105, v98
	v_add_f32_e32 v2, v106, v2
	v_add_f32_e32 v2, v107, v2
	v_add_f32_e32 v2, v108, v2
	v_add_f32_e32 v2, v109, v2
	v_add_f32_e32 v2, v96, v2
	v_add_f32_e32 v2, v97, v2
	v_add_f32_e32 v2, v80, v2
	v_add_f32_e32 v2, v81, v2
	v_add_f32_e32 v2, v82, v2
	v_add_f32_e32 v2, v83, v2
	v_add_f32_e32 v2, v84, v2
	v_add_f32_e32 v2, v85, v2
	v_add_f32_e32 v2, v86, v2
	v_add_f32_e32 v2, v87, v2
	v_add_f32_e32 v2, v88, v2
	v_add_f32_e32 v2, v89, v2
	v_add_f32_e32 v2, v90, v2
	v_add_f32_e32 v2, v91, v2
	v_add_f32_e32 v2, v92, v2
	v_add_f32_e32 v2, v93, v2
	v_add_f32_e32 v2, v94, v2
	s_waitcnt lgkmcnt(0)
	v_mfma_f32_32x32x16_bf16 v[32:47], v[10:13], v[6:9], v[32:47]
	v_add_f32_e32 v10, v95, v2
	v_fmac_f32_e32 v10, v14, v0
	ds_bpermute_b32 v0, v149, v10
	ds_read_b128 v[2:5], v195 offset:31328
	s_waitcnt lgkmcnt(0)
	s_barrier
	s_waitcnt lgkmcnt(1)
	v_add_f32_e32 v0, v10, v0
	s_nop 1
	s_waitcnt lgkmcnt(0)
	v_mfma_f32_32x32x16_bf16 v[16:31], v[2:5], v[6:9], v[16:31]
	v_cmp_ne_u32_e64 s[0:1], 0, v162
	s_nop 4
	v_rcp_f32_e32 v2, v0
	s_nop 0
	v_mul_f32_e32 v80, 1.0, v2
	v_cmp_eq_u32_e32 vcc, 0, v162
	s_and_saveexec_b64 s[4:5], s[0:1]
	s_cbranch_execz .LBB0_226
	v_lshlrev_b32_e32 v2, 14, v153
	v_lshlrev_b32_e32 v3, 2, v155
	v_mul_f32_e32 v0, v64, v80
	v_add3_u32 v2, 0, v2, v3
	v_mul_f32_e32 v3, v65, v80
	ds_write2st64_b32 v2, v0, v3 offset1:1
	v_mul_f32_e32 v0, v66, v80
	v_mul_f32_e32 v3, v67, v80
	ds_write2st64_b32 v2, v0, v3 offset0:2 offset1:3
	v_mul_f32_e32 v0, v68, v80
	v_mul_f32_e32 v3, v69, v80
	ds_write2st64_b32 v2, v0, v3 offset0:4 offset1:5
	v_mul_f32_e32 v0, v70, v80
	v_mul_f32_e32 v3, v71, v80
	ds_write2st64_b32 v2, v0, v3 offset0:6 offset1:7
	v_mul_f32_e32 v0, v72, v80
	v_mul_f32_e32 v3, v73, v80
	ds_write2st64_b32 v2, v0, v3 offset0:8 offset1:9
	v_mul_f32_e32 v0, v74, v80
	v_mul_f32_e32 v3, v75, v80
	ds_write2st64_b32 v2, v0, v3 offset0:10 offset1:11
	v_mul_f32_e32 v0, v76, v80
	v_mul_f32_e32 v3, v77, v80
	ds_write2st64_b32 v2, v0, v3 offset0:12 offset1:13
	v_mul_f32_e32 v0, v78, v80
	v_mul_f32_e32 v3, v79, v80
	ds_write2st64_b32 v2, v0, v3 offset0:14 offset1:15
	v_mul_f32_e32 v0, v48, v80
	v_mul_f32_e32 v3, v49, v80
	ds_write2st64_b32 v2, v0, v3 offset0:16 offset1:17
	v_mul_f32_e32 v0, v50, v80
	v_mul_f32_e32 v3, v51, v80
	ds_write2st64_b32 v2, v0, v3 offset0:18 offset1:19
	v_mul_f32_e32 v0, v52, v80
	v_mul_f32_e32 v3, v53, v80
	ds_write2st64_b32 v2, v0, v3 offset0:20 offset1:21
	v_mul_f32_e32 v0, v54, v80
	v_mul_f32_e32 v3, v55, v80
	ds_write2st64_b32 v2, v0, v3 offset0:22 offset1:23
	v_mul_f32_e32 v0, v56, v80
	v_mul_f32_e32 v3, v57, v80
	ds_write2st64_b32 v2, v0, v3 offset0:24 offset1:25
	v_mul_f32_e32 v0, v58, v80
	v_mul_f32_e32 v3, v59, v80
	ds_write2st64_b32 v2, v0, v3 offset0:26 offset1:27
	v_mul_f32_e32 v0, v60, v80
	v_mul_f32_e32 v3, v61, v80
	ds_write2st64_b32 v2, v0, v3 offset0:28 offset1:29
	v_mul_f32_e32 v0, v62, v80
	v_mul_f32_e32 v3, v63, v80
	ds_write2st64_b32 v2, v0, v3 offset0:30 offset1:31
	v_mul_f32_e32 v0, v32, v80
	v_mul_f32_e32 v3, v33, v80
	ds_write2st64_b32 v2, v0, v3 offset0:32 offset1:33
	v_mul_f32_e32 v0, v34, v80
	v_mul_f32_e32 v3, v35, v80
	ds_write2st64_b32 v2, v0, v3 offset0:34 offset1:35
	v_mul_f32_e32 v0, v36, v80
	v_mul_f32_e32 v3, v37, v80
	ds_write2st64_b32 v2, v0, v3 offset0:36 offset1:37
	v_mul_f32_e32 v0, v38, v80
	v_mul_f32_e32 v3, v39, v80
	ds_write2st64_b32 v2, v0, v3 offset0:38 offset1:39
	v_mul_f32_e32 v0, v40, v80
	v_mul_f32_e32 v3, v41, v80
	ds_write2st64_b32 v2, v0, v3 offset0:40 offset1:41
	v_mul_f32_e32 v0, v42, v80
	v_mul_f32_e32 v3, v43, v80
	ds_write2st64_b32 v2, v0, v3 offset0:42 offset1:43
	v_mul_f32_e32 v0, v44, v80
	v_mul_f32_e32 v3, v45, v80
	ds_write2st64_b32 v2, v0, v3 offset0:44 offset1:45
	v_mul_f32_e32 v0, v46, v80
	v_mul_f32_e32 v3, v47, v80
	ds_write2st64_b32 v2, v0, v3 offset0:46 offset1:47
	v_mul_f32_e32 v0, v16, v80
	v_mul_f32_e32 v3, v17, v80
	ds_write2st64_b32 v2, v0, v3 offset0:48 offset1:49
	v_mul_f32_e32 v0, v18, v80
	v_mul_f32_e32 v3, v19, v80
	ds_write2st64_b32 v2, v0, v3 offset0:50 offset1:51
	v_mul_f32_e32 v0, v20, v80
	v_mul_f32_e32 v3, v21, v80
	ds_write2st64_b32 v2, v0, v3 offset0:52 offset1:53
	v_mul_f32_e32 v0, v22, v80
	v_mul_f32_e32 v3, v23, v80
	ds_write2st64_b32 v2, v0, v3 offset0:54 offset1:55
	v_mul_f32_e32 v0, v24, v80
	v_mul_f32_e32 v3, v25, v80
	ds_write2st64_b32 v2, v0, v3 offset0:56 offset1:57
	v_mul_f32_e32 v0, v26, v80
	v_mul_f32_e32 v3, v27, v80
	ds_write2st64_b32 v2, v0, v3 offset0:58 offset1:59
	v_mul_f32_e32 v0, v28, v80
	v_mul_f32_e32 v3, v29, v80
	ds_write2st64_b32 v2, v0, v3 offset0:60 offset1:61
	v_mul_f32_e32 v0, v30, v80
	v_mul_f32_e32 v3, v31, v80
	ds_write2st64_b32 v2, v0, v3 offset0:62 offset1:63

.LBB0_452:
	v_and_b32_e32 v8, 0xfffffc00, v5
	v_add_u32_e32 v8, v4, v8
	v_ashrrev_i32_e32 v9, 31, v8
	v_lshl_add_u64 v[8:9], v[8:9], 2, s[20:21]
	v_cmp_gt_u32_e32 vcc, 64, v7
	v_add_u32_e32 v5, 0x2000, v5
	s_nop 0
	v_cndmask_b32_e32 v9, v9, v3, vcc
	v_cndmask_b32_e32 v8, v8, v2, vcc
	global_load_dword v8, v[8:9], off
	v_add_u32_e32 v9, 0x200, v7
	v_cmp_lt_i32_e32 vcc, 63, v7
	v_mov_b32_e32 v7, v9
	s_or_b64 s[6:7], vcc, s[6:7]
	s_waitcnt vmcnt(0)
	v_mul_f32_e32 v9, 0xbfb8aa3b, v8
	v_exp_f32_e32 v9, v9
	s_nop 0
	v_add_f32_e32 v9, 1.0, v9
	s_nop 4
	v_rcp_f32_e32 v10, v9
	s_nop 0
	v_mul_f32_e32 v8, v8, v10
	ds_write_b32 v6, v8
	v_add_u32_e32 v6, 0x800, v6
	s_andn2_b64 exec, exec, s[6:7]
	s_cbranch_execnz .LBB0_452
